# v45 with the post-MMA barrier moved 8 MFMAs early (priority 3 on the tail) instead of 4
# baseline (speedup 1.0000x reference)
; #define PG8_STAGE(bufoff, gbase, voff) do { _Pragma("unroll") for (int _i = 0; _i < 2; ++_i) \
;         __builtin_amdgcn_global_load_lds((const unsigned*)((const char*)(gbase) + (voff)[_i]), (PG8_LAS unsigned*)(lds + (bufoff) + ldsw + _i * 8192), 16, 0, 0); } while (0)
; #define PG8_LDA(dst, b, h) do { _Pragma("unroll") for (int m = 0; m < 4; ++m) _Pragma("unroll") for (int k = 0; k < 2; ++k) dst[m][k] = *(const PG8_LAS bf16x8*)(lds + PG8_SA(b, h) + aoff + m * 2048 + k * 1024); } while (0)
; #define PG8_LDB(dst, b, h) do { _Pragma("unroll") for (int n = 0; n < 2; ++n) _Pragma("unroll") for (int k = 0; k < 2; ++k) dst[n][k] = *(const PG8_LAS bf16x8*)(lds + PG8_SB(b, h) + boff + n * 2048 + k * 1024); } while (0)
; #define PG8_MMA(ai, bj, At, Bt) do { __builtin_amdgcn_s_setprio(1); _Pragma("unroll") for (int m = 0; m < 4; ++m) _Pragma("unroll") for (int n = 0; n < 2; ++n) _Pragma("unroll") for (int k = 0; k < 2; ++k) \
;         acc[ai][bj][m][n] = __builtin_amdgcn_mfma_f32_16x16x32_bf16(Bt[n][k], At[m][k], acc[ai][bj][m][n], 0, 0, 0); __builtin_amdgcn_s_setprio(0); } while (0)
; #define PG8_WAIT_V(n) asm volatile("s_waitcnt vmcnt(" #n ")" ::: "memory")
; #define PG8_WAIT_L(n) asm volatile("s_waitcnt lgkmcnt(" #n ")" ::: "memory")
; template <class Epi, class Sched, bool ALIGN_EPI = false, bool SP2 = false>
; __device__ __forceinline__ void gemm_phase(PG8_LAS unsigned char* lds, const Gemm g, const Sched& S, const Epi& E, int wave_in) {
;     ...
;             const bool last = (t == nt - 2);
;             const char* a1 = cA + (size_t)(t + 1) * kstep;
;             const char* a2 = last ? nA : cA + (size_t)(t + 2) * kstep; const char* b2 = last ? nB : cB + (size_t)(t + 2) * kstep;
;             const char* a3 = a2 + kstep; const char* b3 = b2 + kstep;
;             if (last && has_next) S.a_ready(nxt);
;             if constexpr (SP2) {
;             PG8_LDB(B0, 0, 0); PG8_LDB(B1, 0, 1); PG8_SCHED; PG8_LDA(At, 0, 0); PG8_STAGE(PG8_SA(1, 1), a1 + hstep, voffA);
;             PG8_WAIT_V(8); PG8_WAIT_L(0); PG8_BAR; PG8_MMA(0, 0, At, B0); PG8_MMA(0, 1, At, B1); PG8_BAR; PG8_SCHED;
;             PG8_LDA(At, 0, 1); PG8_STAGE(PG8_SB(0, 0), b2, voffB); PG8_STAGE(PG8_SB(0, 1), b2 + hstep, voffB); PG8_STAGE(PG8_SA(0, 0), a2, voffA);
;             PG8_WAIT_V(8); PG8_WAIT_L(0); PG8_BAR; PG8_MMA(1, 0, At, B0); PG8_MMA(1, 1, At, B1); PG8_BAR; PG8_SCHED;
.LBB0_184:
	ds_read_b128 v[144:147], v151
	ds_read_b128 v[154:157], v151 offset:1024
	ds_read_b128 v[158:161], v151 offset:2048
	ds_read_b128 v[162:165], v151 offset:3072
	ds_read_b128 v[168:171], v152
	ds_read_b128 v[172:175], v152 offset:1024
	ds_read_b128 v[176:179], v152 offset:2048
	ds_read_b128 v[180:183], v152 offset:3072
	s_add_u32 s34, s30, 0xfff80080
	s_addc_u32 s35, s31, -1
	s_cmp_eq_u32 s55, 28
	s_cselect_b32 s37, s23, s35
	s_cselect_b32 s36, s50, s34
	s_cselect_b32 s35, s19, s53
	s_cselect_b32 s34, s51, s52
	v_lshl_add_u64 v[166:167], s[30:31], 0, v[136:137]
	s_add_i32 m0, s29, 0xc000
	ds_read_b128 v[184:187], v153
	ds_read_b128 v[188:191], v153 offset:1024
	ds_read_b128 v[192:195], v153 offset:2048
	ds_read_b128 v[196:199], v153 offset:3072
	ds_read_b128 v[200:203], v153 offset:4096
	ds_read_b128 v[204:207], v153 offset:5120
	ds_read_b128 v[208:211], v153 offset:6144
	ds_read_b128 v[212:215], v153 offset:7168
	global_load_lds_dwordx4 v[166:167], off
	v_lshl_add_u64 v[166:167], s[30:31], 0, v[138:139]
	s_add_i32 m0, s29, 0xe000
	s_nop 0
	global_load_lds_dwordx4 v[166:167], off
	s_waitcnt vmcnt(8)
	s_waitcnt lgkmcnt(0)
	s_barrier
	s_setprio 1
	s_waitcnt lgkmcnt(0)
	v_mfma_f32_16x16x32_bf16 v[124:127], v[144:147], v[184:187], v[124:127]
	v_mfma_f32_16x16x32_bf16 v[120:123], v[158:161], v[184:187], v[120:123]
	v_mfma_f32_16x16x32_bf16 v[108:111], v[144:147], v[192:195], v[108:111]
	v_mfma_f32_16x16x32_bf16 v[104:107], v[158:161], v[192:195], v[104:107]
	v_mfma_f32_16x16x32_bf16 v[92:95], v[144:147], v[200:203], v[92:95]
	v_mfma_f32_16x16x32_bf16 v[88:91], v[158:161], v[200:203], v[88:91]
	v_mfma_f32_16x16x32_bf16 v[76:79], v[144:147], v[208:211], v[76:79]
	v_mfma_f32_16x16x32_bf16 v[72:75], v[158:161], v[208:211], v[72:75]
	v_mfma_f32_16x16x32_bf16 v[124:127], v[154:157], v[188:191], v[124:127]
	v_mfma_f32_16x16x32_bf16 v[120:123], v[162:165], v[188:191], v[120:123]
	v_mfma_f32_16x16x32_bf16 v[108:111], v[154:157], v[196:199], v[108:111]
	v_mfma_f32_16x16x32_bf16 v[104:107], v[162:165], v[196:199], v[104:107]
	v_mfma_f32_16x16x32_bf16 v[92:95], v[154:157], v[204:207], v[92:95]
	v_mfma_f32_16x16x32_bf16 v[88:91], v[162:165], v[204:207], v[88:91]
	v_mfma_f32_16x16x32_bf16 v[76:79], v[154:157], v[212:215], v[76:79]
	v_mfma_f32_16x16x32_bf16 v[72:75], v[162:165], v[212:215], v[72:75]
	s_setprio 0
	s_setprio 1
	v_mfma_f32_16x16x32_bf16 v[116:119], v[168:171], v[184:187], v[116:119]
	v_mfma_f32_16x16x32_bf16 v[112:115], v[176:179], v[184:187], v[112:115]
	v_mfma_f32_16x16x32_bf16 v[100:103], v[168:171], v[192:195], v[100:103]
	v_mfma_f32_16x16x32_bf16 v[96:99], v[176:179], v[192:195], v[96:99]
	v_mfma_f32_16x16x32_bf16 v[84:87], v[168:171], v[200:203], v[84:87]
	v_mfma_f32_16x16x32_bf16 v[80:83], v[176:179], v[200:203], v[80:83]
	v_mfma_f32_16x16x32_bf16 v[68:71], v[168:171], v[208:211], v[68:71]
	v_mfma_f32_16x16x32_bf16 v[64:67], v[176:179], v[208:211], v[64:67]
	s_barrier
	s_setprio 3
	v_mfma_f32_16x16x32_bf16 v[116:119], v[172:175], v[188:191], v[116:119]
	v_mfma_f32_16x16x32_bf16 v[112:115], v[180:183], v[188:191], v[112:115]
	v_mfma_f32_16x16x32_bf16 v[100:103], v[172:175], v[196:199], v[100:103]
	v_mfma_f32_16x16x32_bf16 v[96:99], v[180:183], v[196:199], v[96:99]
	v_mfma_f32_16x16x32_bf16 v[84:87], v[172:175], v[204:207], v[84:87]
	v_mfma_f32_16x16x32_bf16 v[80:83], v[180:183], v[204:207], v[80:83]
	v_mfma_f32_16x16x32_bf16 v[68:71], v[172:175], v[212:215], v[68:71]
	v_mfma_f32_16x16x32_bf16 v[64:67], v[180:183], v[212:215], v[64:67]
	s_setprio 0
	s_add_i32 s56, s46, s1
	v_lshl_add_u64 v[166:167], s[34:35], 0, v[132:133]
	s_mov_b32 m0, s56
	ds_read_b128 v[184:187], v153 offset:16384
	ds_read_b128 v[188:191], v153 offset:17408
	ds_read_b128 v[192:195], v153 offset:18432
	ds_read_b128 v[196:199], v153 offset:19456
	ds_read_b128 v[200:203], v153 offset:20480
	ds_read_b128 v[204:207], v153 offset:21504
	ds_read_b128 v[208:211], v153 offset:22528
	ds_read_b128 v[212:215], v153 offset:23552
	global_load_lds_dwordx4 v[166:167], off
	s_add_i32 m0, s56, 0x2000
	s_add_u32 s56, s34, 0x80000
	v_lshl_add_u64 v[216:217], s[34:35], 0, v[128:129]
	s_addc_u32 s57, s35, 0
	s_add_i32 s58, s47, s1
	global_load_lds_dwordx4 v[216:217], off
	v_lshl_add_u64 v[218:219], s[56:57], 0, v[132:133]
	s_mov_b32 m0, s58
	v_lshl_add_u64 v[220:221], s[36:37], 0, v[130:131]
	global_load_lds_dwordx4 v[218:219], off
	v_lshl_add_u64 v[218:219], s[56:57], 0, v[128:129]
	s_add_i32 m0, s58, 0x2000
	s_nop 0
	global_load_lds_dwordx4 v[218:219], off
	v_lshl_add_u64 v[218:219], s[36:37], 0, v[134:135]
	s_mov_b32 m0, s29
	s_nop 0
	global_load_lds_dwordx4 v[218:219], off
	s_mov_b32 m0, s38
	s_nop 0
	global_load_lds_dwordx4 v[220:221], off
	s_waitcnt vmcnt(8)
	s_waitcnt lgkmcnt(0)
	s_barrier
	s_setprio 1
	s_waitcnt lgkmcnt(0)
	v_mfma_f32_16x16x32_bf16 v[60:63], v[144:147], v[184:187], v[60:63]
	v_mfma_f32_16x16x32_bf16 v[56:59], v[158:161], v[184:187], v[56:59]
	v_mfma_f32_16x16x32_bf16 v[44:47], v[144:147], v[192:195], v[44:47]
	v_mfma_f32_16x16x32_bf16 v[40:43], v[158:161], v[192:195], v[40:43]
	v_mfma_f32_16x16x32_bf16 v[28:31], v[144:147], v[200:203], v[28:31]
	v_mfma_f32_16x16x32_bf16 v[24:27], v[158:161], v[200:203], v[24:27]
	v_mfma_f32_16x16x32_bf16 v[12:15], v[144:147], v[208:211], v[12:15]
	v_mfma_f32_16x16x32_bf16 v[8:11], v[158:161], v[208:211], v[8:11]
	v_mfma_f32_16x16x32_bf16 v[60:63], v[154:157], v[188:191], v[60:63]
	v_mfma_f32_16x16x32_bf16 v[56:59], v[162:165], v[188:191], v[56:59]
	v_mfma_f32_16x16x32_bf16 v[44:47], v[154:157], v[196:199], v[44:47]
	v_mfma_f32_16x16x32_bf16 v[40:43], v[162:165], v[196:199], v[40:43]
	v_mfma_f32_16x16x32_bf16 v[28:31], v[154:157], v[204:207], v[28:31]
	v_mfma_f32_16x16x32_bf16 v[24:27], v[162:165], v[204:207], v[24:27]
	v_mfma_f32_16x16x32_bf16 v[12:15], v[154:157], v[212:215], v[12:15]
	v_mfma_f32_16x16x32_bf16 v[8:11], v[162:165], v[212:215], v[8:11]
	s_setprio 0
	s_setprio 1
	v_mfma_f32_16x16x32_bf16 v[52:55], v[168:171], v[184:187], v[52:55]
	v_mfma_f32_16x16x32_bf16 v[48:51], v[176:179], v[184:187], v[48:51]
	v_mfma_f32_16x16x32_bf16 v[36:39], v[168:171], v[192:195], v[36:39]
	v_mfma_f32_16x16x32_bf16 v[32:35], v[176:179], v[192:195], v[32:35]
	v_mfma_f32_16x16x32_bf16 v[20:23], v[168:171], v[200:203], v[20:23]
	v_mfma_f32_16x16x32_bf16 v[16:19], v[176:179], v[200:203], v[16:19]
	v_mfma_f32_16x16x32_bf16 v[4:7], v[168:171], v[208:211], v[4:7]
	v_mfma_f32_16x16x32_bf16 v[0:3], v[176:179], v[208:211], v[0:3]
	s_barrier
; #define PG8_STAGE(bufoff, gbase, voff) do { _Pragma("unroll") for (int _i = 0; _i < 2; ++_i) \
;         __builtin_amdgcn_global_load_lds((const unsigned*)((const char*)(gbase) + (voff)[_i]), (PG8_LAS unsigned*)(lds + (bufoff) + ldsw + _i * 8192), 16, 0, 0); } while (0)
; #define PG8_LDA(dst, b, h) do { _Pragma("unroll") for (int m = 0; m < 4; ++m) _Pragma("unroll") for (int k = 0; k < 2; ++k) dst[m][k] = *(const PG8_LAS bf16x8*)(lds + PG8_SA(b, h) + aoff + m * 2048 + k * 1024); } while (0)
; #define PG8_LDB(dst, b, h) do { _Pragma("unroll") for (int n = 0; n < 2; ++n) _Pragma("unroll") for (int k = 0; k < 2; ++k) dst[n][k] = *(const PG8_LAS bf16x8*)(lds + PG8_SB(b, h) + boff + n * 2048 + k * 1024); } while (0)
; #define PG8_MMA(ai, bj, At, Bt) do { __builtin_amdgcn_s_setprio(1); _Pragma("unroll") for (int m = 0; m < 4; ++m) _Pragma("unroll") for (int n = 0; n < 2; ++n) _Pragma("unroll") for (int k = 0; k < 2; ++k) \
;         acc[ai][bj][m][n] = __builtin_amdgcn_mfma_f32_16x16x32_bf16(Bt[n][k], At[m][k], acc[ai][bj][m][n], 0, 0, 0); __builtin_amdgcn_s_setprio(0); } while (0)
; #define PG8_WAIT_V(n) asm volatile("s_waitcnt vmcnt(" #n ")" ::: "memory")
; #define PG8_WAIT_L(n) asm volatile("s_waitcnt lgkmcnt(" #n ")" ::: "memory")
; #define PG8_BAR __builtin_amdgcn_s_barrier()
; #define PG8_SCHED __builtin_amdgcn_sched_barrier(0)
; template <class Epi, class Sched, bool ALIGN_EPI = false, bool SP2 = false>
; __device__ __forceinline__ void gemm_phase(PG8_LAS unsigned char* lds, const Gemm g, const Sched& S, const Epi& E, int wave_in) {
;     ...
;             PG8_WAIT_V(8); PG8_WAIT_L(0); PG8_BAR; PG8_MMA(1, 0, At, B0); PG8_MMA(1, 1, At, B1); PG8_BAR; PG8_SCHED;
;             PG8_LDB(B0, 1, 0); PG8_LDB(B1, 1, 1); PG8_SCHED; PG8_LDA(At, 1, 0); PG8_STAGE(PG8_SA(0, 1), a2 + hstep, voffA);
;             PG8_WAIT_V(8); PG8_WAIT_L(0); PG8_BAR; PG8_MMA(0, 0, At, B0); PG8_MMA(0, 1, At, B1); PG8_BAR; PG8_SCHED;
	s_setprio 3
	v_mfma_f32_16x16x32_bf16 v[52:55], v[172:175], v[188:191], v[52:55]
	v_mfma_f32_16x16x32_bf16 v[48:51], v[180:183], v[188:191], v[48:51]
	v_mfma_f32_16x16x32_bf16 v[36:39], v[172:175], v[196:199], v[36:39]
	v_mfma_f32_16x16x32_bf16 v[32:35], v[180:183], v[196:199], v[32:35]
	v_mfma_f32_16x16x32_bf16 v[20:23], v[172:175], v[204:207], v[20:23]
	v_mfma_f32_16x16x32_bf16 v[16:19], v[180:183], v[204:207], v[16:19]
	v_mfma_f32_16x16x32_bf16 v[4:7], v[172:175], v[212:215], v[4:7]
	v_mfma_f32_16x16x32_bf16 v[0:3], v[180:183], v[212:215], v[0:3]
	s_setprio 0
	s_add_i32 s56, 0, 0x18000
	s_add_i32 s57, 0, 0x1c000
	v_add_u32_e32 v162, s56, v149
	v_add_u32_e32 v180, s57, v149
	ds_read_b128 v[144:147], v162
	ds_read_b128 v[154:157], v162 offset:1024
	ds_read_b128 v[158:161], v162 offset:2048
	ds_read_b128 v[162:165], v162 offset:3072
	ds_read_b128 v[168:171], v180
	ds_read_b128 v[172:175], v180 offset:1024
	ds_read_b128 v[176:179], v180 offset:2048
	ds_read_b128 v[180:183], v180 offset:3072
	s_add_u32 s36, s36, 0x80000
	s_addc_u32 s37, s37, 0
	s_mov_b32 m0, s39
	v_lshl_add_u64 v[222:223], s[36:37], 0, v[134:135]
	ds_read_b128 v[184:187], v153 offset:32768
	ds_read_b128 v[188:191], v153 offset:33792
	ds_read_b128 v[192:195], v153 offset:34816
	ds_read_b128 v[196:199], v153 offset:35840
	ds_read_b128 v[200:203], v153 offset:36864
	ds_read_b128 v[204:207], v153 offset:37888
	ds_read_b128 v[208:211], v153 offset:38912
	ds_read_b128 v[212:215], v153 offset:39936
	global_load_lds_dwordx4 v[222:223], off
	v_lshl_add_u64 v[222:223], s[36:37], 0, v[130:131]
	s_mov_b32 m0, s40
	s_nop 0
	global_load_lds_dwordx4 v[222:223], off
	s_waitcnt vmcnt(8)
	s_waitcnt lgkmcnt(0)
	s_barrier
	s_setprio 1
	s_waitcnt lgkmcnt(0)
	v_mfma_f32_16x16x32_bf16 v[124:127], v[144:147], v[184:187], v[124:127]
	v_mfma_f32_16x16x32_bf16 v[120:123], v[158:161], v[184:187], v[120:123]
	v_mfma_f32_16x16x32_bf16 v[108:111], v[144:147], v[192:195], v[108:111]
	v_mfma_f32_16x16x32_bf16 v[104:107], v[158:161], v[192:195], v[104:107]
	v_mfma_f32_16x16x32_bf16 v[92:95], v[144:147], v[200:203], v[92:95]
	v_mfma_f32_16x16x32_bf16 v[88:91], v[158:161], v[200:203], v[88:91]
	v_mfma_f32_16x16x32_bf16 v[76:79], v[144:147], v[208:211], v[76:79]
	v_mfma_f32_16x16x32_bf16 v[72:75], v[158:161], v[208:211], v[72:75]
	v_mfma_f32_16x16x32_bf16 v[124:127], v[154:157], v[188:191], v[124:127]
	v_mfma_f32_16x16x32_bf16 v[120:123], v[162:165], v[188:191], v[120:123]
	v_mfma_f32_16x16x32_bf16 v[108:111], v[154:157], v[196:199], v[108:111]
	v_mfma_f32_16x16x32_bf16 v[104:107], v[162:165], v[196:199], v[104:107]
	v_mfma_f32_16x16x32_bf16 v[92:95], v[154:157], v[204:207], v[92:95]
	v_mfma_f32_16x16x32_bf16 v[88:91], v[162:165], v[204:207], v[88:91]
	v_mfma_f32_16x16x32_bf16 v[76:79], v[154:157], v[212:215], v[76:79]
	v_mfma_f32_16x16x32_bf16 v[72:75], v[162:165], v[212:215], v[72:75]
	s_setprio 0
	s_setprio 1
	v_mfma_f32_16x16x32_bf16 v[116:119], v[168:171], v[184:187], v[116:119]
	v_mfma_f32_16x16x32_bf16 v[112:115], v[176:179], v[184:187], v[112:115]
	v_mfma_f32_16x16x32_bf16 v[100:103], v[168:171], v[192:195], v[100:103]
	v_mfma_f32_16x16x32_bf16 v[96:99], v[176:179], v[192:195], v[96:99]
	v_mfma_f32_16x16x32_bf16 v[84:87], v[168:171], v[200:203], v[84:87]
	v_mfma_f32_16x16x32_bf16 v[80:83], v[176:179], v[200:203], v[80:83]
	v_mfma_f32_16x16x32_bf16 v[68:71], v[168:171], v[208:211], v[68:71]
	v_mfma_f32_16x16x32_bf16 v[64:67], v[176:179], v[208:211], v[64:67]
	s_barrier
; #define PG8_STAGE(bufoff, gbase, voff) do { _Pragma("unroll") for (int _i = 0; _i < 2; ++_i) \
;         __builtin_amdgcn_global_load_lds((const unsigned*)((const char*)(gbase) + (voff)[_i]), (PG8_LAS unsigned*)(lds + (bufoff) + ldsw + _i * 8192), 16, 0, 0); } while (0)
; #define PG8_LDA(dst, b, h) do { _Pragma("unroll") for (int m = 0; m < 4; ++m) _Pragma("unroll") for (int k = 0; k < 2; ++k) dst[m][k] = *(const PG8_LAS bf16x8*)(lds + PG8_SA(b, h) + aoff + m * 2048 + k * 1024); } while (0)
; #define PG8_MMA(ai, bj, At, Bt) do { __builtin_amdgcn_s_setprio(1); _Pragma("unroll") for (int m = 0; m < 4; ++m) _Pragma("unroll") for (int n = 0; n < 2; ++n) _Pragma("unroll") for (int k = 0; k < 2; ++k) \
;         acc[ai][bj][m][n] = __builtin_amdgcn_mfma_f32_16x16x32_bf16(Bt[n][k], At[m][k], acc[ai][bj][m][n], 0, 0, 0); __builtin_amdgcn_s_setprio(0); } while (0)
; #define PG8_WAIT_V(n) asm volatile("s_waitcnt vmcnt(" #n ")" ::: "memory")
; #define PG8_WAIT_L(n) asm volatile("s_waitcnt lgkmcnt(" #n ")" ::: "memory")
; #define PG8_BAR __builtin_amdgcn_s_barrier()
; #define PG8_SCHED __builtin_amdgcn_sched_barrier(0)
; template <class Epi, class Sched, bool ALIGN_EPI = false, bool SP2 = false>
; __device__ __forceinline__ void gemm_phase(PG8_LAS unsigned char* lds, const Gemm g, const Sched& S, const Epi& E, int wave_in) {
;     ...
;             PG8_WAIT_V(8); PG8_WAIT_L(0); PG8_BAR; PG8_MMA(0, 0, At, B0); PG8_MMA(0, 1, At, B1); PG8_BAR; PG8_SCHED;
;             PG8_LDA(At, 1, 1); PG8_STAGE(PG8_SB(1, 0), b3, voffB); PG8_STAGE(PG8_SB(1, 1), b3 + hstep, voffB); PG8_STAGE(PG8_SA(1, 0), a3, voffA);
;             PG8_WAIT_V(8); PG8_WAIT_L(0); PG8_BAR; PG8_MMA(1, 0, At, B0); PG8_MMA(1, 1, At, B1); PG8_BAR; PG8_SCHED;
	s_setprio 3
	v_mfma_f32_16x16x32_bf16 v[116:119], v[172:175], v[188:191], v[116:119]
	v_mfma_f32_16x16x32_bf16 v[112:115], v[180:183], v[188:191], v[112:115]
	v_mfma_f32_16x16x32_bf16 v[100:103], v[172:175], v[196:199], v[100:103]
	v_mfma_f32_16x16x32_bf16 v[96:99], v[180:183], v[196:199], v[96:99]
	v_mfma_f32_16x16x32_bf16 v[84:87], v[172:175], v[204:207], v[84:87]
	v_mfma_f32_16x16x32_bf16 v[80:83], v[180:183], v[204:207], v[80:83]
	v_mfma_f32_16x16x32_bf16 v[68:71], v[172:175], v[212:215], v[68:71]
	v_mfma_f32_16x16x32_bf16 v[64:67], v[180:183], v[212:215], v[64:67]
	s_setprio 0
	s_add_i32 s36, s56, s1
	v_lshl_add_u64 v[166:167], v[166:167], 0, s[10:11]
	s_mov_b32 m0, s36
	ds_read_b128 v[184:187], v153 offset:49152
	ds_read_b128 v[188:191], v153 offset:50176
	ds_read_b128 v[192:195], v153 offset:51200
	ds_read_b128 v[196:199], v153 offset:52224
	ds_read_b128 v[200:203], v153 offset:53248
	ds_read_b128 v[204:207], v153 offset:54272
	ds_read_b128 v[208:211], v153 offset:55296
	ds_read_b128 v[212:215], v153 offset:56320
	global_load_lds_dwordx4 v[166:167], off
	s_add_i32 m0, s36, 0x2000
	s_add_u32 s34, s34, 0x80080
	v_lshl_add_u64 v[166:167], v[216:217], 0, s[10:11]
	s_addc_u32 s35, s35, 0
	s_add_i32 s36, s57, s1
	global_load_lds_dwordx4 v[166:167], off
	v_lshl_add_u64 v[166:167], s[34:35], 0, v[132:133]
	s_mov_b32 m0, s36
	s_nop 0
	global_load_lds_dwordx4 v[166:167], off
	v_lshl_add_u64 v[166:167], s[34:35], 0, v[128:129]
	s_add_i32 m0, s36, 0x2000
	s_nop 0
	global_load_lds_dwordx4 v[166:167], off
	v_lshl_add_u64 v[166:167], v[218:219], 0, s[10:11]
	s_mov_b32 m0, s42
	s_nop 0
	global_load_lds_dwordx4 v[166:167], off
	v_lshl_add_u64 v[166:167], v[220:221], 0, s[10:11]
	s_mov_b32 m0, s43
	s_nop 0
	global_load_lds_dwordx4 v[166:167], off
	s_waitcnt vmcnt(8)
	s_waitcnt lgkmcnt(0)
	s_barrier
	s_setprio 1
	s_waitcnt lgkmcnt(0)
	v_mfma_f32_16x16x32_bf16 v[60:63], v[144:147], v[184:187], v[60:63]
	v_mfma_f32_16x16x32_bf16 v[56:59], v[158:161], v[184:187], v[56:59]
	v_mfma_f32_16x16x32_bf16 v[44:47], v[144:147], v[192:195], v[44:47]
	v_mfma_f32_16x16x32_bf16 v[40:43], v[158:161], v[192:195], v[40:43]
	v_mfma_f32_16x16x32_bf16 v[28:31], v[144:147], v[200:203], v[28:31]
	v_mfma_f32_16x16x32_bf16 v[24:27], v[158:161], v[200:203], v[24:27]
	v_mfma_f32_16x16x32_bf16 v[12:15], v[144:147], v[208:211], v[12:15]
	v_mfma_f32_16x16x32_bf16 v[8:11], v[158:161], v[208:211], v[8:11]
	v_mfma_f32_16x16x32_bf16 v[60:63], v[154:157], v[188:191], v[60:63]
	v_mfma_f32_16x16x32_bf16 v[56:59], v[162:165], v[188:191], v[56:59]
	v_mfma_f32_16x16x32_bf16 v[44:47], v[154:157], v[196:199], v[44:47]
	v_mfma_f32_16x16x32_bf16 v[40:43], v[162:165], v[196:199], v[40:43]
	v_mfma_f32_16x16x32_bf16 v[28:31], v[154:157], v[204:207], v[28:31]
	v_mfma_f32_16x16x32_bf16 v[24:27], v[162:165], v[204:207], v[24:27]
	v_mfma_f32_16x16x32_bf16 v[12:15], v[154:157], v[212:215], v[12:15]
	v_mfma_f32_16x16x32_bf16 v[8:11], v[162:165], v[212:215], v[8:11]
	s_setprio 0
	s_setprio 1
	v_mfma_f32_16x16x32_bf16 v[52:55], v[168:171], v[184:187], v[52:55]
	v_mfma_f32_16x16x32_bf16 v[48:51], v[176:179], v[184:187], v[48:51]
	v_mfma_f32_16x16x32_bf16 v[36:39], v[168:171], v[192:195], v[36:39]
	v_mfma_f32_16x16x32_bf16 v[32:35], v[176:179], v[192:195], v[32:35]
	v_mfma_f32_16x16x32_bf16 v[20:23], v[168:171], v[200:203], v[20:23]
	v_mfma_f32_16x16x32_bf16 v[16:19], v[176:179], v[200:203], v[16:19]
	v_mfma_f32_16x16x32_bf16 v[4:7], v[168:171], v[208:211], v[4:7]
	v_mfma_f32_16x16x32_bf16 v[0:3], v[176:179], v[208:211], v[0:3]
	s_barrier
	s_setprio 3
	v_mfma_f32_16x16x32_bf16 v[52:55], v[172:175], v[188:191], v[52:55]
	v_mfma_f32_16x16x32_bf16 v[48:51], v[180:183], v[188:191], v[48:51]
	v_mfma_f32_16x16x32_bf16 v[36:39], v[172:175], v[196:199], v[36:39]
	v_mfma_f32_16x16x32_bf16 v[32:35], v[180:183], v[196:199], v[32:35]
	v_mfma_f32_16x16x32_bf16 v[20:23], v[172:175], v[204:207], v[20:23]
	v_mfma_f32_16x16x32_bf16 v[16:19], v[180:183], v[204:207], v[16:19]
	v_mfma_f32_16x16x32_bf16 v[4:7], v[172:175], v[212:215], v[4:7]
	v_mfma_f32_16x16x32_bf16 v[0:3], v[180:183], v[212:215], v[0:3]
	s_setprio 0
	s_add_i32 s55, s55, 2
	s_add_u32 s30, s30, 0x100
	s_addc_u32 s31, s31, 0
	s_add_u32 s52, s52, 0x100
	s_addc_u32 s53, s53, 0
	s_cmp_gt_u32 s55, 29
	s_cbranch_scc0 .LBB0_184
	s_and_b64 vcc, exec, s[16:17]
	s_cbranch_vccz .LBB0_187
	s_barrier

; #define PG8_STAGE(bufoff, gbase, voff) do { _Pragma("unroll") for (int _i = 0; _i < 2; ++_i) \
;         __builtin_amdgcn_global_load_lds((const unsigned*)((const char*)(gbase) + (voff)[_i]), (PG8_LAS unsigned*)(lds + (bufoff) + ldsw + _i * 8192), 16, 0, 0); } while (0)
; #define PG8_LDA(dst, b, h) do { _Pragma("unroll") for (int m = 0; m < 4; ++m) _Pragma("unroll") for (int k = 0; k < 2; ++k) dst[m][k] = *(const PG8_LAS bf16x8*)(lds + PG8_SA(b, h) + aoff + m * 2048 + k * 1024); } while (0)
; #define PG8_LDB(dst, b, h) do { _Pragma("unroll") for (int n = 0; n < 2; ++n) _Pragma("unroll") for (int k = 0; k < 2; ++k) dst[n][k] = *(const PG8_LAS bf16x8*)(lds + PG8_SB(b, h) + boff + n * 2048 + k * 1024); } while (0)
; #define PG8_MMA(ai, bj, At, Bt) do { __builtin_amdgcn_s_setprio(1); _Pragma("unroll") for (int m = 0; m < 4; ++m) _Pragma("unroll") for (int n = 0; n < 2; ++n) _Pragma("unroll") for (int k = 0; k < 2; ++k) \
;         acc[ai][bj][m][n] = __builtin_amdgcn_mfma_f32_16x16x32_bf16(Bt[n][k], At[m][k], acc[ai][bj][m][n], 0, 0, 0); __builtin_amdgcn_s_setprio(0); } while (0)
; #define PG8_WAIT_V(n) asm volatile("s_waitcnt vmcnt(" #n ")" ::: "memory")
; #define PG8_WAIT_L(n) asm volatile("s_waitcnt lgkmcnt(" #n ")" ::: "memory")
; template <class Epi, class Sched, bool ALIGN_EPI = false, bool SP2 = false>
; __device__ __forceinline__ void gemm_phase(PG8_LAS unsigned char* lds, const Gemm g, const Sched& S, const Epi& E, int wave_in) {
;     ...
;             const bool last = (t == nt - 2);
;             const char* a1 = cA + (size_t)(t + 1) * kstep;
;             const char* a2 = last ? nA : cA + (size_t)(t + 2) * kstep; const char* b2 = last ? nB : cB + (size_t)(t + 2) * kstep;
;             const char* a3 = a2 + kstep; const char* b3 = b2 + kstep;
;             if (last && has_next) S.a_ready(nxt);
;             if constexpr (SP2) {
;             PG8_LDB(B0, 0, 0); PG8_LDB(B1, 0, 1); PG8_SCHED; PG8_LDA(At, 0, 0); PG8_STAGE(PG8_SA(1, 1), a1 + hstep, voffA);
;             PG8_WAIT_V(8); PG8_WAIT_L(0); PG8_BAR; PG8_MMA(0, 0, At, B0); PG8_MMA(0, 1, At, B1); PG8_BAR; PG8_SCHED;
;             PG8_LDA(At, 0, 1); PG8_STAGE(PG8_SB(0, 0), b2, voffB); PG8_STAGE(PG8_SB(0, 1), b2 + hstep, voffB); PG8_STAGE(PG8_SA(0, 0), a2, voffA);
;             PG8_WAIT_V(8); PG8_WAIT_L(0); PG8_BAR; PG8_MMA(1, 0, At, B0); PG8_MMA(1, 1, At, B1); PG8_BAR; PG8_SCHED;
.LBB0_307:
	ds_read_b128 v[140:143], v147
	ds_read_b128 v[152:155], v147 offset:1024
	ds_read_b128 v[156:159], v147 offset:2048
	ds_read_b128 v[160:163], v147 offset:3072
	ds_read_b128 v[168:171], v148
	ds_read_b128 v[172:175], v148 offset:1024
	ds_read_b128 v[176:179], v148 offset:2048
	ds_read_b128 v[180:183], v148 offset:3072
	s_add_u32 s28, s26, 0x100
	s_addc_u32 s29, s27, 0
	s_cmpk_eq_i32 s55, 0x54
	s_cselect_b32 s35, s5, s29
	s_cselect_b32 s34, s4, s28
	s_cselect_b32 s31, s25, s54
	s_cselect_b32 s30, s24, s53
	v_lshl_add_u64 v[164:165], s[26:27], 0, v[132:133]
	s_add_i32 m0, s37, 0xc000
	ds_read_b128 v[184:187], v149
	ds_read_b128 v[188:191], v149 offset:1024
	ds_read_b128 v[192:195], v149 offset:2048
	ds_read_b128 v[196:199], v149 offset:3072
	ds_read_b128 v[200:203], v149 offset:4096
	ds_read_b128 v[204:207], v149 offset:5120
	ds_read_b128 v[208:211], v149 offset:6144
	ds_read_b128 v[212:215], v149 offset:7168
	global_load_lds_dwordx4 v[164:165], off
	v_lshl_add_u64 v[164:165], s[26:27], 0, v[134:135]
	s_add_i32 m0, s37, 0xe000
	s_nop 0
	global_load_lds_dwordx4 v[164:165], off
	s_waitcnt vmcnt(8)
	s_waitcnt lgkmcnt(0)
	s_barrier
	s_setprio 1
	s_waitcnt lgkmcnt(0)
	v_mfma_f32_16x16x32_bf16 v[124:127], v[140:143], v[184:187], v[124:127]
	v_mfma_f32_16x16x32_bf16 v[120:123], v[156:159], v[184:187], v[120:123]
	v_mfma_f32_16x16x32_bf16 v[108:111], v[140:143], v[192:195], v[108:111]
	v_mfma_f32_16x16x32_bf16 v[104:107], v[156:159], v[192:195], v[104:107]
	v_mfma_f32_16x16x32_bf16 v[92:95], v[140:143], v[200:203], v[92:95]
	v_mfma_f32_16x16x32_bf16 v[88:91], v[156:159], v[200:203], v[88:91]
	v_mfma_f32_16x16x32_bf16 v[76:79], v[140:143], v[208:211], v[76:79]
	v_mfma_f32_16x16x32_bf16 v[72:75], v[156:159], v[208:211], v[72:75]
	v_mfma_f32_16x16x32_bf16 v[124:127], v[152:155], v[188:191], v[124:127]
	v_mfma_f32_16x16x32_bf16 v[120:123], v[160:163], v[188:191], v[120:123]
	v_mfma_f32_16x16x32_bf16 v[108:111], v[152:155], v[196:199], v[108:111]
	v_mfma_f32_16x16x32_bf16 v[104:107], v[160:163], v[196:199], v[104:107]
	v_mfma_f32_16x16x32_bf16 v[92:95], v[152:155], v[204:207], v[92:95]
	v_mfma_f32_16x16x32_bf16 v[88:91], v[160:163], v[204:207], v[88:91]
	v_mfma_f32_16x16x32_bf16 v[76:79], v[152:155], v[212:215], v[76:79]
	v_mfma_f32_16x16x32_bf16 v[72:75], v[160:163], v[212:215], v[72:75]
	s_setprio 0
	s_setprio 1
	v_mfma_f32_16x16x32_bf16 v[116:119], v[168:171], v[184:187], v[116:119]
	v_mfma_f32_16x16x32_bf16 v[112:115], v[176:179], v[184:187], v[112:115]
	v_mfma_f32_16x16x32_bf16 v[100:103], v[168:171], v[192:195], v[100:103]
	v_mfma_f32_16x16x32_bf16 v[96:99], v[176:179], v[192:195], v[96:99]
	v_mfma_f32_16x16x32_bf16 v[84:87], v[168:171], v[200:203], v[84:87]
	v_mfma_f32_16x16x32_bf16 v[80:83], v[176:179], v[200:203], v[80:83]
	v_mfma_f32_16x16x32_bf16 v[68:71], v[168:171], v[208:211], v[68:71]
	v_mfma_f32_16x16x32_bf16 v[64:67], v[176:179], v[208:211], v[64:67]
	s_barrier
	s_setprio 3
	v_mfma_f32_16x16x32_bf16 v[116:119], v[172:175], v[188:191], v[116:119]
	v_mfma_f32_16x16x32_bf16 v[112:115], v[180:183], v[188:191], v[112:115]
	v_mfma_f32_16x16x32_bf16 v[100:103], v[172:175], v[196:199], v[100:103]
	v_mfma_f32_16x16x32_bf16 v[96:99], v[180:183], v[196:199], v[96:99]
	v_mfma_f32_16x16x32_bf16 v[84:87], v[172:175], v[204:207], v[84:87]
	v_mfma_f32_16x16x32_bf16 v[80:83], v[180:183], v[204:207], v[80:83]
	v_mfma_f32_16x16x32_bf16 v[68:71], v[172:175], v[212:215], v[68:71]
	v_mfma_f32_16x16x32_bf16 v[64:67], v[180:183], v[212:215], v[64:67]
	s_setprio 0
	s_add_i32 s26, s47, s21
	v_lshl_add_u64 v[164:165], s[30:31], 0, v[128:129]
	s_mov_b32 m0, s26
	ds_read_b128 v[184:187], v149 offset:16384
	ds_read_b128 v[188:191], v149 offset:17408
	ds_read_b128 v[192:195], v149 offset:18432
	ds_read_b128 v[196:199], v149 offset:19456
	ds_read_b128 v[200:203], v149 offset:20480
	ds_read_b128 v[204:207], v149 offset:21504
	ds_read_b128 v[208:211], v149 offset:22528
	ds_read_b128 v[212:215], v149 offset:23552
	global_load_lds_dwordx4 v[164:165], off
	s_add_i32 m0, s26, 0x2000
	s_add_u32 s26, s30, 0x160000
	v_lshl_add_u64 v[166:167], s[30:31], 0, v[130:131]
	s_addc_u32 s27, s31, 0
	s_add_i32 s56, s48, s21
	global_load_lds_dwordx4 v[166:167], off
	v_lshl_add_u64 v[216:217], s[26:27], 0, v[128:129]
	s_mov_b32 m0, s56
	v_lshl_add_u64 v[218:219], s[34:35], 0, v[130:131]
	global_load_lds_dwordx4 v[216:217], off
	v_lshl_add_u64 v[216:217], s[26:27], 0, v[130:131]
	s_add_i32 m0, s56, 0x2000
	s_nop 0
	global_load_lds_dwordx4 v[216:217], off
	v_lshl_add_u64 v[216:217], s[34:35], 0, v[128:129]
	s_mov_b32 m0, s37
	s_nop 0
	global_load_lds_dwordx4 v[216:217], off
	s_mov_b32 m0, s38
	s_nop 0
	global_load_lds_dwordx4 v[218:219], off
	s_waitcnt vmcnt(8)
	s_waitcnt lgkmcnt(0)
	s_barrier
	s_setprio 1
	s_waitcnt lgkmcnt(0)
	v_mfma_f32_16x16x32_bf16 v[60:63], v[140:143], v[184:187], v[60:63]
	v_mfma_f32_16x16x32_bf16 v[56:59], v[156:159], v[184:187], v[56:59]
	v_mfma_f32_16x16x32_bf16 v[44:47], v[140:143], v[192:195], v[44:47]
	v_mfma_f32_16x16x32_bf16 v[40:43], v[156:159], v[192:195], v[40:43]
	v_mfma_f32_16x16x32_bf16 v[28:31], v[140:143], v[200:203], v[28:31]
	v_mfma_f32_16x16x32_bf16 v[24:27], v[156:159], v[200:203], v[24:27]
	v_mfma_f32_16x16x32_bf16 v[12:15], v[140:143], v[208:211], v[12:15]
	v_mfma_f32_16x16x32_bf16 v[8:11], v[156:159], v[208:211], v[8:11]
	v_mfma_f32_16x16x32_bf16 v[60:63], v[152:155], v[188:191], v[60:63]
	v_mfma_f32_16x16x32_bf16 v[56:59], v[160:163], v[188:191], v[56:59]
	v_mfma_f32_16x16x32_bf16 v[44:47], v[152:155], v[196:199], v[44:47]
	v_mfma_f32_16x16x32_bf16 v[40:43], v[160:163], v[196:199], v[40:43]
	v_mfma_f32_16x16x32_bf16 v[28:31], v[152:155], v[204:207], v[28:31]
	v_mfma_f32_16x16x32_bf16 v[24:27], v[160:163], v[204:207], v[24:27]
	v_mfma_f32_16x16x32_bf16 v[12:15], v[152:155], v[212:215], v[12:15]
	v_mfma_f32_16x16x32_bf16 v[8:11], v[160:163], v[212:215], v[8:11]
	s_setprio 0
	s_setprio 1
	v_mfma_f32_16x16x32_bf16 v[52:55], v[168:171], v[184:187], v[52:55]
	v_mfma_f32_16x16x32_bf16 v[48:51], v[176:179], v[184:187], v[48:51]
	v_mfma_f32_16x16x32_bf16 v[36:39], v[168:171], v[192:195], v[36:39]
	v_mfma_f32_16x16x32_bf16 v[32:35], v[176:179], v[192:195], v[32:35]
	v_mfma_f32_16x16x32_bf16 v[20:23], v[168:171], v[200:203], v[20:23]
	v_mfma_f32_16x16x32_bf16 v[16:19], v[176:179], v[200:203], v[16:19]
	v_mfma_f32_16x16x32_bf16 v[4:7], v[168:171], v[208:211], v[4:7]
	v_mfma_f32_16x16x32_bf16 v[0:3], v[176:179], v[208:211], v[0:3]
	s_barrier
; #define PG8_STAGE(bufoff, gbase, voff) do { _Pragma("unroll") for (int _i = 0; _i < 2; ++_i) \
;         __builtin_amdgcn_global_load_lds((const unsigned*)((const char*)(gbase) + (voff)[_i]), (PG8_LAS unsigned*)(lds + (bufoff) + ldsw + _i * 8192), 16, 0, 0); } while (0)
; #define PG8_LDA(dst, b, h) do { _Pragma("unroll") for (int m = 0; m < 4; ++m) _Pragma("unroll") for (int k = 0; k < 2; ++k) dst[m][k] = *(const PG8_LAS bf16x8*)(lds + PG8_SA(b, h) + aoff + m * 2048 + k * 1024); } while (0)
; #define PG8_LDB(dst, b, h) do { _Pragma("unroll") for (int n = 0; n < 2; ++n) _Pragma("unroll") for (int k = 0; k < 2; ++k) dst[n][k] = *(const PG8_LAS bf16x8*)(lds + PG8_SB(b, h) + boff + n * 2048 + k * 1024); } while (0)
; #define PG8_MMA(ai, bj, At, Bt) do { __builtin_amdgcn_s_setprio(1); _Pragma("unroll") for (int m = 0; m < 4; ++m) _Pragma("unroll") for (int n = 0; n < 2; ++n) _Pragma("unroll") for (int k = 0; k < 2; ++k) \
;         acc[ai][bj][m][n] = __builtin_amdgcn_mfma_f32_16x16x32_bf16(Bt[n][k], At[m][k], acc[ai][bj][m][n], 0, 0, 0); __builtin_amdgcn_s_setprio(0); } while (0)
; #define PG8_WAIT_V(n) asm volatile("s_waitcnt vmcnt(" #n ")" ::: "memory")
; #define PG8_WAIT_L(n) asm volatile("s_waitcnt lgkmcnt(" #n ")" ::: "memory")
; #define PG8_BAR __builtin_amdgcn_s_barrier()
; #define PG8_SCHED __builtin_amdgcn_sched_barrier(0)
; template <class Epi, class Sched, bool ALIGN_EPI = false, bool SP2 = false>
; __device__ __forceinline__ void gemm_phase(PG8_LAS unsigned char* lds, const Gemm g, const Sched& S, const Epi& E, int wave_in) {
;     ...
;             PG8_LDB(B0, 1, 0); PG8_LDB(B1, 1, 1); PG8_SCHED; PG8_LDA(At, 1, 0); PG8_STAGE(PG8_SA(0, 1), a2 + hstep, voffA);
;             PG8_WAIT_V(8); PG8_WAIT_L(0); PG8_BAR; PG8_MMA(0, 0, At, B0); PG8_MMA(0, 1, At, B1); PG8_BAR; PG8_SCHED;
;             PG8_LDA(At, 1, 1); PG8_STAGE(PG8_SB(1, 0), b3, voffB); PG8_STAGE(PG8_SB(1, 1), b3 + hstep, voffB); PG8_STAGE(PG8_SA(1, 0), a3, voffA);
	s_setprio 3
	v_mfma_f32_16x16x32_bf16 v[52:55], v[172:175], v[188:191], v[52:55]
	v_mfma_f32_16x16x32_bf16 v[48:51], v[180:183], v[188:191], v[48:51]
	v_mfma_f32_16x16x32_bf16 v[36:39], v[172:175], v[196:199], v[36:39]
	v_mfma_f32_16x16x32_bf16 v[32:35], v[180:183], v[196:199], v[32:35]
	v_mfma_f32_16x16x32_bf16 v[20:23], v[172:175], v[204:207], v[20:23]
	v_mfma_f32_16x16x32_bf16 v[16:19], v[180:183], v[204:207], v[16:19]
	v_mfma_f32_16x16x32_bf16 v[4:7], v[172:175], v[212:215], v[4:7]
	v_mfma_f32_16x16x32_bf16 v[0:3], v[180:183], v[212:215], v[0:3]
	s_setprio 0
	s_add_i32 s56, 0, 0x18000
	v_add_u32_e32 v151, s56, v145
	s_add_i32 s57, 0, 0x1c000
	ds_read_b128 v[140:143], v151
	ds_read_b128 v[152:155], v151 offset:1024
	ds_read_b128 v[156:159], v151 offset:2048
	ds_read_b128 v[160:163], v151 offset:3072
	v_add_u32_e32 v151, s57, v145
	ds_read_b128 v[168:171], v151
	ds_read_b128 v[172:175], v151 offset:1024
	ds_read_b128 v[176:179], v151 offset:2048
	ds_read_b128 v[180:183], v151 offset:3072
	s_add_u32 s26, s34, 0x160000
	s_addc_u32 s27, s35, 0
	s_mov_b32 m0, s39
	v_lshl_add_u64 v[220:221], s[26:27], 0, v[128:129]
	ds_read_b128 v[184:187], v149 offset:32768
	ds_read_b128 v[188:191], v149 offset:33792
	ds_read_b128 v[192:195], v149 offset:34816
	ds_read_b128 v[196:199], v149 offset:35840
	ds_read_b128 v[200:203], v149 offset:36864
	ds_read_b128 v[204:207], v149 offset:37888
	ds_read_b128 v[208:211], v149 offset:38912
	ds_read_b128 v[212:215], v149 offset:39936
	global_load_lds_dwordx4 v[220:221], off
	v_lshl_add_u64 v[220:221], s[26:27], 0, v[130:131]
	s_mov_b32 m0, s40
	s_nop 0
	global_load_lds_dwordx4 v[220:221], off
	s_waitcnt vmcnt(8)
	s_waitcnt lgkmcnt(0)
	s_barrier
	s_setprio 1
	s_waitcnt lgkmcnt(0)
	v_mfma_f32_16x16x32_bf16 v[124:127], v[140:143], v[184:187], v[124:127]
	v_mfma_f32_16x16x32_bf16 v[120:123], v[156:159], v[184:187], v[120:123]
	v_mfma_f32_16x16x32_bf16 v[108:111], v[140:143], v[192:195], v[108:111]
	v_mfma_f32_16x16x32_bf16 v[104:107], v[156:159], v[192:195], v[104:107]
	v_mfma_f32_16x16x32_bf16 v[92:95], v[140:143], v[200:203], v[92:95]
	v_mfma_f32_16x16x32_bf16 v[88:91], v[156:159], v[200:203], v[88:91]
	v_mfma_f32_16x16x32_bf16 v[76:79], v[140:143], v[208:211], v[76:79]
	v_mfma_f32_16x16x32_bf16 v[72:75], v[156:159], v[208:211], v[72:75]
	v_mfma_f32_16x16x32_bf16 v[124:127], v[152:155], v[188:191], v[124:127]
	v_mfma_f32_16x16x32_bf16 v[120:123], v[160:163], v[188:191], v[120:123]
	v_mfma_f32_16x16x32_bf16 v[108:111], v[152:155], v[196:199], v[108:111]
	v_mfma_f32_16x16x32_bf16 v[104:107], v[160:163], v[196:199], v[104:107]
	v_mfma_f32_16x16x32_bf16 v[92:95], v[152:155], v[204:207], v[92:95]
	v_mfma_f32_16x16x32_bf16 v[88:91], v[160:163], v[204:207], v[88:91]
	v_mfma_f32_16x16x32_bf16 v[76:79], v[152:155], v[212:215], v[76:79]
	v_mfma_f32_16x16x32_bf16 v[72:75], v[160:163], v[212:215], v[72:75]
	s_setprio 0
	s_setprio 1
	v_mfma_f32_16x16x32_bf16 v[116:119], v[168:171], v[184:187], v[116:119]
	v_mfma_f32_16x16x32_bf16 v[112:115], v[176:179], v[184:187], v[112:115]
	v_mfma_f32_16x16x32_bf16 v[100:103], v[168:171], v[192:195], v[100:103]
	v_mfma_f32_16x16x32_bf16 v[96:99], v[176:179], v[192:195], v[96:99]
	v_mfma_f32_16x16x32_bf16 v[84:87], v[168:171], v[200:203], v[84:87]
	v_mfma_f32_16x16x32_bf16 v[80:83], v[176:179], v[200:203], v[80:83]
	v_mfma_f32_16x16x32_bf16 v[68:71], v[168:171], v[208:211], v[68:71]
	v_mfma_f32_16x16x32_bf16 v[64:67], v[176:179], v[208:211], v[64:67]
	s_barrier
	s_setprio 3
	v_mfma_f32_16x16x32_bf16 v[116:119], v[172:175], v[188:191], v[116:119]
	v_mfma_f32_16x16x32_bf16 v[112:115], v[180:183], v[188:191], v[112:115]
	v_mfma_f32_16x16x32_bf16 v[100:103], v[172:175], v[196:199], v[100:103]
	v_mfma_f32_16x16x32_bf16 v[96:99], v[180:183], v[196:199], v[96:99]
	v_mfma_f32_16x16x32_bf16 v[84:87], v[172:175], v[204:207], v[84:87]
	v_mfma_f32_16x16x32_bf16 v[80:83], v[180:183], v[204:207], v[80:83]
	v_mfma_f32_16x16x32_bf16 v[68:71], v[172:175], v[212:215], v[68:71]
	v_mfma_f32_16x16x32_bf16 v[64:67], v[180:183], v[212:215], v[64:67]
	s_setprio 0
	s_add_i32 s26, s56, s21
	v_lshl_add_u64 v[164:165], v[164:165], 0, s[10:11]
	s_mov_b32 m0, s26
	ds_read_b128 v[184:187], v149 offset:49152
	ds_read_b128 v[188:191], v149 offset:50176
	ds_read_b128 v[192:195], v149 offset:51200
	ds_read_b128 v[196:199], v149 offset:52224
	ds_read_b128 v[200:203], v149 offset:53248
	ds_read_b128 v[204:207], v149 offset:54272
	ds_read_b128 v[208:211], v149 offset:55296
	ds_read_b128 v[212:215], v149 offset:56320
	global_load_lds_dwordx4 v[164:165], off
	s_add_i32 m0, s26, 0x2000
	s_add_u32 s26, s30, 0x160080
	v_lshl_add_u64 v[164:165], v[166:167], 0, s[10:11]
	s_addc_u32 s27, s31, 0
	s_add_i32 s30, s57, s21
	global_load_lds_dwordx4 v[164:165], off
	v_lshl_add_u64 v[164:165], s[26:27], 0, v[128:129]
	s_mov_b32 m0, s30
	s_nop 0
	global_load_lds_dwordx4 v[164:165], off
	v_lshl_add_u64 v[164:165], s[26:27], 0, v[130:131]
	s_add_i32 m0, s30, 0x2000
	s_nop 0
	global_load_lds_dwordx4 v[164:165], off
	v_lshl_add_u64 v[164:165], v[216:217], 0, s[10:11]
	s_mov_b32 m0, s42
	s_nop 0
	global_load_lds_dwordx4 v[164:165], off
	v_lshl_add_u64 v[164:165], v[218:219], 0, s[10:11]
	s_mov_b32 m0, s43
	s_nop 0
	global_load_lds_dwordx4 v[164:165], off
	s_waitcnt vmcnt(8)
	s_waitcnt lgkmcnt(0)
	s_barrier
; #define PG8_STAGE(bufoff, gbase, voff) do { _Pragma("unroll") for (int _i = 0; _i < 2; ++_i) \
;         __builtin_amdgcn_global_load_lds((const unsigned*)((const char*)(gbase) + (voff)[_i]), (PG8_LAS unsigned*)(lds + (bufoff) + ldsw + _i * 8192), 16, 0, 0); } while (0)
; #define PG8_LDA(dst, b, h) do { _Pragma("unroll") for (int m = 0; m < 4; ++m) _Pragma("unroll") for (int k = 0; k < 2; ++k) dst[m][k] = *(const PG8_LAS bf16x8*)(lds + PG8_SA(b, h) + aoff + m * 2048 + k * 1024); } while (0)
; #define PG8_MMA(ai, bj, At, Bt) do { __builtin_amdgcn_s_setprio(1); _Pragma("unroll") for (int m = 0; m < 4; ++m) _Pragma("unroll") for (int n = 0; n < 2; ++n) _Pragma("unroll") for (int k = 0; k < 2; ++k) \
;         acc[ai][bj][m][n] = __builtin_amdgcn_mfma_f32_16x16x32_bf16(Bt[n][k], At[m][k], acc[ai][bj][m][n], 0, 0, 0); __builtin_amdgcn_s_setprio(0); } while (0)
; #define PG8_WAIT_V(n) asm volatile("s_waitcnt vmcnt(" #n ")" ::: "memory")
; #define PG8_BAR __builtin_amdgcn_s_barrier()
;     __device__ __forceinline__ void operator()(const f32x4 (&acc)[2][2][4][2], const Unit& u, int wr, int wc, int fr, int fq) const {
;     ...
;             for (int m = 0; m < 4; ++m) { const int row = u.pm * BM + ai * HALF + wr * 64 + m * 16 + fr; const size_t off = (size_t)row * ldc + col0;
;                 float ss = 0.f;
; #pragma unroll
;                 for (int bj = 0; bj < 2; ++bj)
; #pragma unroll
;                     for (int n = 0; n < 2; ++n) { f32x4 bs;
;                         if (BASE_BF16) { const u32x2 t = *(const u32x2*)((const bf16_t*)base + off + bj * HALF + n * 16);
;                             bs = (f32x4){__builtin_bit_cast(float, t.x << 16), __builtin_bit_cast(float, t.x & 0xffff0000u), __builtin_bit_cast(float, t.y << 16), __builtin_bit_cast(float, t.y & 0xffff0000u)}; }
;                         else bs = *(const f32x4*)((const float*)base + off + bj * HALF + n * 16);
; template <class Epi, class Sched, bool ALIGN_EPI = false, bool SP2 = false>
; __device__ __forceinline__ void gemm_phase(PG8_LAS unsigned char* lds, const Gemm g, const Sched& S, const Epi& E, int wave_in) {
;     ...
;             PG8_LDA(At, 1, 1); PG8_STAGE(PG8_SB(1, 0), b3, voffB); PG8_STAGE(PG8_SB(1, 1), b3 + hstep, voffB); PG8_STAGE(PG8_SA(1, 0), a3, voffA);
;             PG8_WAIT_V(8); PG8_WAIT_L(0); PG8_BAR; PG8_MMA(1, 0, At, B0); PG8_MMA(1, 1, At, B1); PG8_BAR; PG8_SCHED;
	s_setprio 1
	s_waitcnt lgkmcnt(0)
	v_mfma_f32_16x16x32_bf16 v[60:63], v[140:143], v[184:187], v[60:63]
	v_mfma_f32_16x16x32_bf16 v[56:59], v[156:159], v[184:187], v[56:59]
	v_mfma_f32_16x16x32_bf16 v[44:47], v[140:143], v[192:195], v[44:47]
	v_mfma_f32_16x16x32_bf16 v[40:43], v[156:159], v[192:195], v[40:43]
	v_mfma_f32_16x16x32_bf16 v[28:31], v[140:143], v[200:203], v[28:31]
	v_mfma_f32_16x16x32_bf16 v[24:27], v[156:159], v[200:203], v[24:27]
	v_mfma_f32_16x16x32_bf16 v[12:15], v[140:143], v[208:211], v[12:15]
	v_mfma_f32_16x16x32_bf16 v[8:11], v[156:159], v[208:211], v[8:11]
	v_mfma_f32_16x16x32_bf16 v[60:63], v[152:155], v[188:191], v[60:63]
	v_mfma_f32_16x16x32_bf16 v[56:59], v[160:163], v[188:191], v[56:59]
	v_mfma_f32_16x16x32_bf16 v[44:47], v[152:155], v[196:199], v[44:47]
	v_mfma_f32_16x16x32_bf16 v[40:43], v[160:163], v[196:199], v[40:43]
	v_mfma_f32_16x16x32_bf16 v[28:31], v[152:155], v[204:207], v[28:31]
	v_mfma_f32_16x16x32_bf16 v[24:27], v[160:163], v[204:207], v[24:27]
	v_mfma_f32_16x16x32_bf16 v[12:15], v[152:155], v[212:215], v[12:15]
	v_mfma_f32_16x16x32_bf16 v[8:11], v[160:163], v[212:215], v[8:11]
	s_setprio 0
	s_setprio 1
	v_mfma_f32_16x16x32_bf16 v[52:55], v[168:171], v[184:187], v[52:55]
	v_mfma_f32_16x16x32_bf16 v[48:51], v[176:179], v[184:187], v[48:51]
	v_mfma_f32_16x16x32_bf16 v[36:39], v[168:171], v[192:195], v[36:39]
	v_mfma_f32_16x16x32_bf16 v[32:35], v[176:179], v[192:195], v[32:35]
	v_mfma_f32_16x16x32_bf16 v[20:23], v[168:171], v[200:203], v[20:23]
	v_mfma_f32_16x16x32_bf16 v[16:19], v[176:179], v[200:203], v[16:19]
	v_mfma_f32_16x16x32_bf16 v[4:7], v[168:171], v[208:211], v[4:7]
	v_mfma_f32_16x16x32_bf16 v[0:3], v[176:179], v[208:211], v[0:3]
	s_barrier
	s_setprio 3
	v_mfma_f32_16x16x32_bf16 v[52:55], v[172:175], v[188:191], v[52:55]
	v_mfma_f32_16x16x32_bf16 v[48:51], v[180:183], v[188:191], v[48:51]
	v_mfma_f32_16x16x32_bf16 v[36:39], v[172:175], v[196:199], v[36:39]
	v_mfma_f32_16x16x32_bf16 v[32:35], v[180:183], v[196:199], v[32:35]
	v_mfma_f32_16x16x32_bf16 v[20:23], v[172:175], v[204:207], v[20:23]
	v_mfma_f32_16x16x32_bf16 v[16:19], v[180:183], v[204:207], v[16:19]
	v_mfma_f32_16x16x32_bf16 v[4:7], v[172:175], v[212:215], v[4:7]
	v_mfma_f32_16x16x32_bf16 v[0:3], v[180:183], v[212:215], v[0:3]
	s_setprio 0
	s_add_i32 s55, s55, 2
	s_add_u32 s53, s53, 0x100
	s_addc_u32 s54, s54, 0
	s_cmpk_gt_u32 s55, 0x55
	s_mov_b64 s[26:27], s[28:29]
	s_cbranch_scc0 .LBB0_307
	v_lshl_add_u32 v142, s51, 8, v144
	v_lshl_or_b32 v140, s52, 8, v146
	v_ashrrev_i32_e32 v143, 31, v142
	v_ashrrev_i32_e32 v141, 31, v140
	v_xor_b32_e32 v212, 16, v150
	v_xor_b32_e32 v213, 32, v150
	v_lshlrev_b32_e32 v212, 2, v212
	v_lshlrev_b32_e32 v213, 2, v213
	v_mov_b32_e32 v152, v142
	v_ashrrev_i32_e32 v153, 31, v152
	v_lshlrev_b64 v[154:155], 11, v[152:153]
	v_lshl_add_u64 v[154:155], v[154:155], 0, v[140:141]
	v_lshl_add_u64 v[156:157], v[154:155], 2, s[0:1]
	global_load_dwordx4 v[164:167], v[156:157], off
	global_load_dwordx4 v[168:171], v[156:157], off offset:64
	global_load_dwordx4 v[172:175], v[156:157], off offset:512
	global_load_dwordx4 v[176:179], v[156:157], off offset:576
	v_add_u32_e32 v152, 16, v142
	v_ashrrev_i32_e32 v153, 31, v152
	v_lshlrev_b64 v[154:155], 11, v[152:153]
	v_lshl_add_u64 v[154:155], v[154:155], 0, v[140:141]
	v_lshl_add_u64 v[156:157], v[154:155], 2, s[0:1]
	global_load_dwordx4 v[180:183], v[156:157], off
	global_load_dwordx4 v[184:187], v[156:157], off offset:64
	global_load_dwordx4 v[188:191], v[156:157], off offset:512
	global_load_dwordx4 v[192:195], v[156:157], off offset:576
	v_add_u32_e32 v152, 32, v142
	v_ashrrev_i32_e32 v153, 31, v152
	v_lshlrev_b64 v[154:155], 11, v[152:153]
	v_lshl_add_u64 v[154:155], v[154:155], 0, v[140:141]
	v_lshl_add_u64 v[156:157], v[154:155], 2, s[0:1]
	global_load_dwordx4 v[196:199], v[156:157], off
	global_load_dwordx4 v[200:203], v[156:157], off offset:64
	global_load_dwordx4 v[204:207], v[156:157], off offset:512
	global_load_dwordx4 v[208:211], v[156:157], off offset:576
	s_and_b64 vcc, exec, s[18:19]
	s_cbranch_vccz .LBB0_310
	s_barrier

; #define PG8_STAGE(bufoff, gbase, voff) do { _Pragma("unroll") for (int _i = 0; _i < 2; ++_i) \
;         __builtin_amdgcn_global_load_lds((const unsigned*)((const char*)(gbase) + (voff)[_i]), (PG8_LAS unsigned*)(lds + (bufoff) + ldsw + _i * 8192), 16, 0, 0); } while (0)
; #define PG8_LDA(dst, b, h) do { _Pragma("unroll") for (int m = 0; m < 4; ++m) _Pragma("unroll") for (int k = 0; k < 2; ++k) dst[m][k] = *(const PG8_LAS bf16x8*)(lds + PG8_SA(b, h) + aoff + m * 2048 + k * 1024); } while (0)
; #define PG8_LDB(dst, b, h) do { _Pragma("unroll") for (int n = 0; n < 2; ++n) _Pragma("unroll") for (int k = 0; k < 2; ++k) dst[n][k] = *(const PG8_LAS bf16x8*)(lds + PG8_SB(b, h) + boff + n * 2048 + k * 1024); } while (0)
; #define PG8_MMA(ai, bj, At, Bt) do { __builtin_amdgcn_s_setprio(1); _Pragma("unroll") for (int m = 0; m < 4; ++m) _Pragma("unroll") for (int n = 0; n < 2; ++n) _Pragma("unroll") for (int k = 0; k < 2; ++k) \
;         acc[ai][bj][m][n] = __builtin_amdgcn_mfma_f32_16x16x32_bf16(Bt[n][k], At[m][k], acc[ai][bj][m][n], 0, 0, 0); __builtin_amdgcn_s_setprio(0); } while (0)
; #define PG8_WAIT_V(n) asm volatile("s_waitcnt vmcnt(" #n ")" ::: "memory")
; #define PG8_WAIT_L(n) asm volatile("s_waitcnt lgkmcnt(" #n ")" ::: "memory")
; template <class Epi, class Sched, bool ALIGN_EPI = false, bool SP2 = false>
; __device__ __forceinline__ void gemm_phase(PG8_LAS unsigned char* lds, const Gemm g, const Sched& S, const Epi& E, int wave_in) {
;     ...
;             const bool last = (t == nt - 2);
;             const char* a1 = cA + (size_t)(t + 1) * kstep;
;             const char* a2 = last ? nA : cA + (size_t)(t + 2) * kstep; const char* b2 = last ? nB : cB + (size_t)(t + 2) * kstep;
;             const char* a3 = a2 + kstep; const char* b3 = b2 + kstep;
;             if (last && has_next) S.a_ready(nxt);
;             if constexpr (SP2) {
;             PG8_LDB(B0, 0, 0); PG8_LDB(B1, 0, 1); PG8_SCHED; PG8_LDA(At, 0, 0); PG8_STAGE(PG8_SA(1, 1), a1 + hstep, voffA);
;             PG8_WAIT_V(8); PG8_WAIT_L(0); PG8_BAR; PG8_MMA(0, 0, At, B0); PG8_MMA(0, 1, At, B1); PG8_BAR; PG8_SCHED;
;             PG8_LDA(At, 0, 1); PG8_STAGE(PG8_SB(0, 0), b2, voffB); PG8_STAGE(PG8_SB(0, 1), b2 + hstep, voffB); PG8_STAGE(PG8_SA(0, 0), a2, voffA);
;             PG8_WAIT_V(8); PG8_WAIT_L(0); PG8_BAR; PG8_MMA(1, 0, At, B0); PG8_MMA(1, 1, At, B1); PG8_BAR; PG8_SCHED;
.LBB0_393:
	ds_read_b128 v[148:151], v159
	ds_read_b128 v[152:155], v159 offset:1024
	ds_read_b128 v[168:171], v159 offset:2048
	ds_read_b128 v[172:175], v159 offset:3072
	ds_read_b128 v[176:179], v160
	ds_read_b128 v[180:183], v160 offset:1024
	ds_read_b128 v[184:187], v160 offset:2048
	ds_read_b128 v[188:191], v160 offset:3072
	s_add_u32 s10, s8, 0xfff80080
	s_addc_u32 s11, s9, -1
	s_cmp_eq_u32 s42, 28
	s_cselect_b32 s39, s5, s11
	s_cselect_b32 s38, s31, s10
	s_cselect_b32 s11, s29, s41
	s_cselect_b32 s10, s33, s40
	v_lshl_add_u64 v[156:157], s[8:9], 0, v[140:141]
	s_add_i32 m0, s48, 0xc000
	ds_read_b128 v[192:195], v161
	ds_read_b128 v[196:199], v161 offset:1024
	ds_read_b128 v[200:203], v161 offset:2048
	ds_read_b128 v[204:207], v161 offset:3072
	ds_read_b128 v[208:211], v161 offset:4096
	ds_read_b128 v[212:215], v161 offset:5120
	ds_read_b128 v[216:219], v161 offset:6144
	ds_read_b128 v[220:223], v161 offset:7168
	global_load_lds_dwordx4 v[156:157], off
	v_lshl_add_u64 v[156:157], s[8:9], 0, v[142:143]
	s_add_i32 m0, s48, 0xe000
	s_nop 0
	global_load_lds_dwordx4 v[156:157], off
	s_waitcnt vmcnt(8)
	s_waitcnt lgkmcnt(0)
	s_barrier
	s_setprio 1
	s_waitcnt lgkmcnt(0)
	v_mfma_f32_16x16x32_bf16 v[124:127], v[148:151], v[192:195], v[124:127]
	v_mfma_f32_16x16x32_bf16 v[120:123], v[168:171], v[192:195], v[120:123]
	v_mfma_f32_16x16x32_bf16 v[108:111], v[148:151], v[200:203], v[108:111]
	v_mfma_f32_16x16x32_bf16 v[104:107], v[168:171], v[200:203], v[104:107]
	v_mfma_f32_16x16x32_bf16 v[92:95], v[148:151], v[208:211], v[92:95]
	v_mfma_f32_16x16x32_bf16 v[88:91], v[168:171], v[208:211], v[88:91]
	v_mfma_f32_16x16x32_bf16 v[76:79], v[148:151], v[216:219], v[76:79]
	v_mfma_f32_16x16x32_bf16 v[72:75], v[168:171], v[216:219], v[72:75]
	v_mfma_f32_16x16x32_bf16 v[124:127], v[152:155], v[196:199], v[124:127]
	v_mfma_f32_16x16x32_bf16 v[120:123], v[172:175], v[196:199], v[120:123]
	v_mfma_f32_16x16x32_bf16 v[108:111], v[152:155], v[204:207], v[108:111]
	v_mfma_f32_16x16x32_bf16 v[104:107], v[172:175], v[204:207], v[104:107]
	v_mfma_f32_16x16x32_bf16 v[92:95], v[152:155], v[212:215], v[92:95]
	v_mfma_f32_16x16x32_bf16 v[88:91], v[172:175], v[212:215], v[88:91]
	v_mfma_f32_16x16x32_bf16 v[76:79], v[152:155], v[220:223], v[76:79]
	v_mfma_f32_16x16x32_bf16 v[72:75], v[172:175], v[220:223], v[72:75]
	s_setprio 0
	s_setprio 1
	v_mfma_f32_16x16x32_bf16 v[116:119], v[176:179], v[192:195], v[116:119]
	v_mfma_f32_16x16x32_bf16 v[112:115], v[184:187], v[192:195], v[112:115]
	v_mfma_f32_16x16x32_bf16 v[100:103], v[176:179], v[200:203], v[100:103]
	v_mfma_f32_16x16x32_bf16 v[96:99], v[184:187], v[200:203], v[96:99]
	v_mfma_f32_16x16x32_bf16 v[84:87], v[176:179], v[208:211], v[84:87]
	v_mfma_f32_16x16x32_bf16 v[80:83], v[184:187], v[208:211], v[80:83]
	v_mfma_f32_16x16x32_bf16 v[68:71], v[176:179], v[216:219], v[68:71]
	v_mfma_f32_16x16x32_bf16 v[64:67], v[184:187], v[216:219], v[64:67]
	s_barrier
	s_setprio 3
	v_mfma_f32_16x16x32_bf16 v[116:119], v[180:183], v[196:199], v[116:119]
	v_mfma_f32_16x16x32_bf16 v[112:115], v[188:191], v[196:199], v[112:115]
	v_mfma_f32_16x16x32_bf16 v[100:103], v[180:183], v[204:207], v[100:103]
	v_mfma_f32_16x16x32_bf16 v[96:99], v[188:191], v[204:207], v[96:99]
	v_mfma_f32_16x16x32_bf16 v[84:87], v[180:183], v[212:215], v[84:87]
	v_mfma_f32_16x16x32_bf16 v[80:83], v[188:191], v[212:215], v[80:83]
	v_mfma_f32_16x16x32_bf16 v[68:71], v[180:183], v[220:223], v[68:71]
	v_mfma_f32_16x16x32_bf16 v[64:67], v[188:191], v[220:223], v[64:67]
	s_setprio 0
	s_add_i32 s43, s61, s21
	v_lshl_add_u64 v[156:157], s[10:11], 0, v[130:131]
	s_mov_b32 m0, s43
	ds_read_b128 v[192:195], v161 offset:16384
	ds_read_b128 v[196:199], v161 offset:17408
	ds_read_b128 v[200:203], v161 offset:18432
	ds_read_b128 v[204:207], v161 offset:19456
	ds_read_b128 v[208:211], v161 offset:20480
	ds_read_b128 v[212:215], v161 offset:21504
	ds_read_b128 v[216:219], v161 offset:22528
	ds_read_b128 v[220:223], v161 offset:23552
	global_load_lds_dwordx4 v[156:157], off
	s_add_i32 m0, s43, 0x2000
	s_add_u32 s44, s10, 0x80000
	v_lshl_add_u64 v[164:165], s[10:11], 0, v[134:135]
	s_addc_u32 s45, s11, 0
	s_add_i32 s43, s62, s21
	global_load_lds_dwordx4 v[164:165], off
	v_lshl_add_u64 v[166:167], s[44:45], 0, v[130:131]
	s_mov_b32 m0, s43
	v_lshl_add_u64 v[224:225], s[38:39], 0, v[132:133]
	global_load_lds_dwordx4 v[166:167], off
	v_lshl_add_u64 v[166:167], s[44:45], 0, v[134:135]
	s_add_i32 m0, s43, 0x2000
	s_nop 0
	global_load_lds_dwordx4 v[166:167], off
	v_lshl_add_u64 v[166:167], s[38:39], 0, v[128:129]
	s_mov_b32 m0, s48
	s_nop 0
	global_load_lds_dwordx4 v[166:167], off
	s_mov_b32 m0, s49
	s_nop 0
	global_load_lds_dwordx4 v[224:225], off
	s_waitcnt vmcnt(8)
	s_waitcnt lgkmcnt(0)
	s_barrier
	s_setprio 1
	s_waitcnt lgkmcnt(0)
	v_mfma_f32_16x16x32_bf16 v[60:63], v[148:151], v[192:195], v[60:63]
	v_mfma_f32_16x16x32_bf16 v[56:59], v[168:171], v[192:195], v[56:59]
	v_mfma_f32_16x16x32_bf16 v[44:47], v[148:151], v[200:203], v[44:47]
	v_mfma_f32_16x16x32_bf16 v[40:43], v[168:171], v[200:203], v[40:43]
	v_mfma_f32_16x16x32_bf16 v[28:31], v[148:151], v[208:211], v[28:31]
	v_mfma_f32_16x16x32_bf16 v[24:27], v[168:171], v[208:211], v[24:27]
	v_mfma_f32_16x16x32_bf16 v[12:15], v[148:151], v[216:219], v[12:15]
	v_mfma_f32_16x16x32_bf16 v[8:11], v[168:171], v[216:219], v[8:11]
	v_mfma_f32_16x16x32_bf16 v[60:63], v[152:155], v[196:199], v[60:63]
	v_mfma_f32_16x16x32_bf16 v[56:59], v[172:175], v[196:199], v[56:59]
	v_mfma_f32_16x16x32_bf16 v[44:47], v[152:155], v[204:207], v[44:47]
	v_mfma_f32_16x16x32_bf16 v[40:43], v[172:175], v[204:207], v[40:43]
	v_mfma_f32_16x16x32_bf16 v[28:31], v[152:155], v[212:215], v[28:31]
	v_mfma_f32_16x16x32_bf16 v[24:27], v[172:175], v[212:215], v[24:27]
	v_mfma_f32_16x16x32_bf16 v[12:15], v[152:155], v[220:223], v[12:15]
	v_mfma_f32_16x16x32_bf16 v[8:11], v[172:175], v[220:223], v[8:11]
	s_setprio 0
	s_setprio 1
	v_mfma_f32_16x16x32_bf16 v[52:55], v[176:179], v[192:195], v[52:55]
	v_mfma_f32_16x16x32_bf16 v[48:51], v[184:187], v[192:195], v[48:51]
	v_mfma_f32_16x16x32_bf16 v[36:39], v[176:179], v[200:203], v[36:39]
	v_mfma_f32_16x16x32_bf16 v[32:35], v[184:187], v[200:203], v[32:35]
	v_mfma_f32_16x16x32_bf16 v[20:23], v[176:179], v[208:211], v[20:23]
	v_mfma_f32_16x16x32_bf16 v[16:19], v[184:187], v[208:211], v[16:19]
	v_mfma_f32_16x16x32_bf16 v[4:7], v[176:179], v[216:219], v[4:7]
	v_mfma_f32_16x16x32_bf16 v[0:3], v[184:187], v[216:219], v[0:3]
	s_barrier
; #define PG8_STAGE(bufoff, gbase, voff) do { _Pragma("unroll") for (int _i = 0; _i < 2; ++_i) \
;         __builtin_amdgcn_global_load_lds((const unsigned*)((const char*)(gbase) + (voff)[_i]), (PG8_LAS unsigned*)(lds + (bufoff) + ldsw + _i * 8192), 16, 0, 0); } while (0)
; #define PG8_LDA(dst, b, h) do { _Pragma("unroll") for (int m = 0; m < 4; ++m) _Pragma("unroll") for (int k = 0; k < 2; ++k) dst[m][k] = *(const PG8_LAS bf16x8*)(lds + PG8_SA(b, h) + aoff + m * 2048 + k * 1024); } while (0)
; #define PG8_LDB(dst, b, h) do { _Pragma("unroll") for (int n = 0; n < 2; ++n) _Pragma("unroll") for (int k = 0; k < 2; ++k) dst[n][k] = *(const PG8_LAS bf16x8*)(lds + PG8_SB(b, h) + boff + n * 2048 + k * 1024); } while (0)
; #define PG8_MMA(ai, bj, At, Bt) do { __builtin_amdgcn_s_setprio(1); _Pragma("unroll") for (int m = 0; m < 4; ++m) _Pragma("unroll") for (int n = 0; n < 2; ++n) _Pragma("unroll") for (int k = 0; k < 2; ++k) \
;         acc[ai][bj][m][n] = __builtin_amdgcn_mfma_f32_16x16x32_bf16(Bt[n][k], At[m][k], acc[ai][bj][m][n], 0, 0, 0); __builtin_amdgcn_s_setprio(0); } while (0)
; #define PG8_WAIT_V(n) asm volatile("s_waitcnt vmcnt(" #n ")" ::: "memory")
; #define PG8_WAIT_L(n) asm volatile("s_waitcnt lgkmcnt(" #n ")" ::: "memory")
; #define PG8_BAR __builtin_amdgcn_s_barrier()
; #define PG8_SCHED __builtin_amdgcn_sched_barrier(0)
; template <class Epi, class Sched, bool ALIGN_EPI = false, bool SP2 = false>
; __device__ __forceinline__ void gemm_phase(PG8_LAS unsigned char* lds, const Gemm g, const Sched& S, const Epi& E, int wave_in) {
;     ...
;             PG8_WAIT_V(8); PG8_WAIT_L(0); PG8_BAR; PG8_MMA(1, 0, At, B0); PG8_MMA(1, 1, At, B1); PG8_BAR; PG8_SCHED;
;             PG8_LDB(B0, 1, 0); PG8_LDB(B1, 1, 1); PG8_SCHED; PG8_LDA(At, 1, 0); PG8_STAGE(PG8_SA(0, 1), a2 + hstep, voffA);
;             PG8_WAIT_V(8); PG8_WAIT_L(0); PG8_BAR; PG8_MMA(0, 0, At, B0); PG8_MMA(0, 1, At, B1); PG8_BAR; PG8_SCHED;
	s_setprio 3
	v_mfma_f32_16x16x32_bf16 v[52:55], v[180:183], v[196:199], v[52:55]
	v_mfma_f32_16x16x32_bf16 v[48:51], v[188:191], v[196:199], v[48:51]
	v_mfma_f32_16x16x32_bf16 v[36:39], v[180:183], v[204:207], v[36:39]
	v_mfma_f32_16x16x32_bf16 v[32:35], v[188:191], v[204:207], v[32:35]
	v_mfma_f32_16x16x32_bf16 v[20:23], v[180:183], v[212:215], v[20:23]
	v_mfma_f32_16x16x32_bf16 v[16:19], v[188:191], v[212:215], v[16:19]
	v_mfma_f32_16x16x32_bf16 v[4:7], v[180:183], v[220:223], v[4:7]
	v_mfma_f32_16x16x32_bf16 v[0:3], v[188:191], v[220:223], v[0:3]
	s_setprio 0
	s_add_i32 s43, 0, 0x18000
	v_add_u32_e32 v136, s43, v158
	s_add_i32 s44, 0, 0x1c000
	ds_read_b128 v[148:151], v136
	ds_read_b128 v[152:155], v136 offset:1024
	ds_read_b128 v[168:171], v136 offset:2048
	ds_read_b128 v[172:175], v136 offset:3072
	v_add_u32_e32 v136, s44, v158
	ds_read_b128 v[176:179], v136
	ds_read_b128 v[180:183], v136 offset:1024
	ds_read_b128 v[184:187], v136 offset:2048
	ds_read_b128 v[188:191], v136 offset:3072
	s_add_u32 s38, s38, 0x80000
	s_addc_u32 s39, s39, 0
	s_mov_b32 m0, s50
	v_lshl_add_u64 v[226:227], s[38:39], 0, v[128:129]
	ds_read_b128 v[192:195], v161 offset:32768
	ds_read_b128 v[196:199], v161 offset:33792
	ds_read_b128 v[200:203], v161 offset:34816
	ds_read_b128 v[204:207], v161 offset:35840
	ds_read_b128 v[208:211], v161 offset:36864
	ds_read_b128 v[212:215], v161 offset:37888
	ds_read_b128 v[216:219], v161 offset:38912
	ds_read_b128 v[220:223], v161 offset:39936
	global_load_lds_dwordx4 v[226:227], off
	v_lshl_add_u64 v[226:227], s[38:39], 0, v[132:133]
	s_mov_b32 m0, s51
	s_nop 0
	global_load_lds_dwordx4 v[226:227], off
	s_waitcnt vmcnt(8)
	s_waitcnt lgkmcnt(0)
	s_barrier
	s_setprio 1
	s_waitcnt lgkmcnt(0)
	v_mfma_f32_16x16x32_bf16 v[124:127], v[148:151], v[192:195], v[124:127]
	v_mfma_f32_16x16x32_bf16 v[120:123], v[168:171], v[192:195], v[120:123]
	v_mfma_f32_16x16x32_bf16 v[108:111], v[148:151], v[200:203], v[108:111]
	v_mfma_f32_16x16x32_bf16 v[104:107], v[168:171], v[200:203], v[104:107]
	v_mfma_f32_16x16x32_bf16 v[92:95], v[148:151], v[208:211], v[92:95]
	v_mfma_f32_16x16x32_bf16 v[88:91], v[168:171], v[208:211], v[88:91]
	v_mfma_f32_16x16x32_bf16 v[76:79], v[148:151], v[216:219], v[76:79]
	v_mfma_f32_16x16x32_bf16 v[72:75], v[168:171], v[216:219], v[72:75]
	v_mfma_f32_16x16x32_bf16 v[124:127], v[152:155], v[196:199], v[124:127]
	v_mfma_f32_16x16x32_bf16 v[120:123], v[172:175], v[196:199], v[120:123]
	v_mfma_f32_16x16x32_bf16 v[108:111], v[152:155], v[204:207], v[108:111]
	v_mfma_f32_16x16x32_bf16 v[104:107], v[172:175], v[204:207], v[104:107]
	v_mfma_f32_16x16x32_bf16 v[92:95], v[152:155], v[212:215], v[92:95]
	v_mfma_f32_16x16x32_bf16 v[88:91], v[172:175], v[212:215], v[88:91]
	v_mfma_f32_16x16x32_bf16 v[76:79], v[152:155], v[220:223], v[76:79]
	v_mfma_f32_16x16x32_bf16 v[72:75], v[172:175], v[220:223], v[72:75]
	s_setprio 0
	s_setprio 1
	v_mfma_f32_16x16x32_bf16 v[116:119], v[176:179], v[192:195], v[116:119]
	v_mfma_f32_16x16x32_bf16 v[112:115], v[184:187], v[192:195], v[112:115]
	v_mfma_f32_16x16x32_bf16 v[100:103], v[176:179], v[200:203], v[100:103]
	v_mfma_f32_16x16x32_bf16 v[96:99], v[184:187], v[200:203], v[96:99]
	v_mfma_f32_16x16x32_bf16 v[84:87], v[176:179], v[208:211], v[84:87]
	v_mfma_f32_16x16x32_bf16 v[80:83], v[184:187], v[208:211], v[80:83]
	v_mfma_f32_16x16x32_bf16 v[68:71], v[176:179], v[216:219], v[68:71]
	v_mfma_f32_16x16x32_bf16 v[64:67], v[184:187], v[216:219], v[64:67]
	s_barrier
; #define PG8_STAGE(bufoff, gbase, voff) do { _Pragma("unroll") for (int _i = 0; _i < 2; ++_i) \
;         __builtin_amdgcn_global_load_lds((const unsigned*)((const char*)(gbase) + (voff)[_i]), (PG8_LAS unsigned*)(lds + (bufoff) + ldsw + _i * 8192), 16, 0, 0); } while (0)
; #define PG8_LDA(dst, b, h) do { _Pragma("unroll") for (int m = 0; m < 4; ++m) _Pragma("unroll") for (int k = 0; k < 2; ++k) dst[m][k] = *(const PG8_LAS bf16x8*)(lds + PG8_SA(b, h) + aoff + m * 2048 + k * 1024); } while (0)
; #define PG8_MMA(ai, bj, At, Bt) do { __builtin_amdgcn_s_setprio(1); _Pragma("unroll") for (int m = 0; m < 4; ++m) _Pragma("unroll") for (int n = 0; n < 2; ++n) _Pragma("unroll") for (int k = 0; k < 2; ++k) \
;         acc[ai][bj][m][n] = __builtin_amdgcn_mfma_f32_16x16x32_bf16(Bt[n][k], At[m][k], acc[ai][bj][m][n], 0, 0, 0); __builtin_amdgcn_s_setprio(0); } while (0)
; #define PG8_WAIT_V(n) asm volatile("s_waitcnt vmcnt(" #n ")" ::: "memory")
; #define PG8_WAIT_L(n) asm volatile("s_waitcnt lgkmcnt(" #n ")" ::: "memory")
; #define PG8_BAR __builtin_amdgcn_s_barrier()
; #define PG8_SCHED __builtin_amdgcn_sched_barrier(0)
; template <class Epi, class Sched, bool ALIGN_EPI = false, bool SP2 = false>
; __device__ __forceinline__ void gemm_phase(PG8_LAS unsigned char* lds, const Gemm g, const Sched& S, const Epi& E, int wave_in) {
;     ...
;             PG8_WAIT_V(8); PG8_WAIT_L(0); PG8_BAR; PG8_MMA(0, 0, At, B0); PG8_MMA(0, 1, At, B1); PG8_BAR; PG8_SCHED;
;             PG8_LDA(At, 1, 1); PG8_STAGE(PG8_SB(1, 0), b3, voffB); PG8_STAGE(PG8_SB(1, 1), b3 + hstep, voffB); PG8_STAGE(PG8_SA(1, 0), a3, voffA);
;             PG8_WAIT_V(8); PG8_WAIT_L(0); PG8_BAR; PG8_MMA(1, 0, At, B0); PG8_MMA(1, 1, At, B1); PG8_BAR; PG8_SCHED;
	s_setprio 3
	v_mfma_f32_16x16x32_bf16 v[116:119], v[180:183], v[196:199], v[116:119]
	v_mfma_f32_16x16x32_bf16 v[112:115], v[188:191], v[196:199], v[112:115]
	v_mfma_f32_16x16x32_bf16 v[100:103], v[180:183], v[204:207], v[100:103]
	v_mfma_f32_16x16x32_bf16 v[96:99], v[188:191], v[204:207], v[96:99]
	v_mfma_f32_16x16x32_bf16 v[84:87], v[180:183], v[212:215], v[84:87]
	v_mfma_f32_16x16x32_bf16 v[80:83], v[188:191], v[212:215], v[80:83]
	v_mfma_f32_16x16x32_bf16 v[68:71], v[180:183], v[220:223], v[68:71]
	v_mfma_f32_16x16x32_bf16 v[64:67], v[188:191], v[220:223], v[64:67]
	s_setprio 0
	s_add_i32 s38, s43, s21
	v_lshl_add_u64 v[156:157], v[156:157], 0, s[18:19]
	s_mov_b32 m0, s38
	ds_read_b128 v[192:195], v161 offset:49152
	ds_read_b128 v[196:199], v161 offset:50176
	ds_read_b128 v[200:203], v161 offset:51200
	ds_read_b128 v[204:207], v161 offset:52224
	ds_read_b128 v[208:211], v161 offset:53248
	ds_read_b128 v[212:215], v161 offset:54272
	ds_read_b128 v[216:219], v161 offset:55296
	ds_read_b128 v[220:223], v161 offset:56320
	global_load_lds_dwordx4 v[156:157], off
	s_add_i32 m0, s38, 0x2000
	s_add_u32 s10, s10, 0x80080
	v_lshl_add_u64 v[156:157], v[164:165], 0, s[18:19]
	s_addc_u32 s11, s11, 0
	s_add_i32 s38, s44, s21
	global_load_lds_dwordx4 v[156:157], off
	v_lshl_add_u64 v[156:157], s[10:11], 0, v[130:131]
	s_mov_b32 m0, s38
	s_nop 0
	global_load_lds_dwordx4 v[156:157], off
	v_lshl_add_u64 v[156:157], s[10:11], 0, v[134:135]
	s_add_i32 m0, s38, 0x2000
	s_nop 0
	global_load_lds_dwordx4 v[156:157], off
	v_lshl_add_u64 v[156:157], v[166:167], 0, s[18:19]
	s_mov_b32 m0, s55
	s_nop 0
	global_load_lds_dwordx4 v[156:157], off
	v_lshl_add_u64 v[156:157], v[224:225], 0, s[18:19]
	s_mov_b32 m0, s56
	s_nop 0
	global_load_lds_dwordx4 v[156:157], off
	s_waitcnt vmcnt(8)
	s_waitcnt lgkmcnt(0)
	s_barrier
	s_setprio 1
	s_waitcnt lgkmcnt(0)
	v_mfma_f32_16x16x32_bf16 v[60:63], v[148:151], v[192:195], v[60:63]
	v_mfma_f32_16x16x32_bf16 v[56:59], v[168:171], v[192:195], v[56:59]
	v_mfma_f32_16x16x32_bf16 v[44:47], v[148:151], v[200:203], v[44:47]
	v_mfma_f32_16x16x32_bf16 v[40:43], v[168:171], v[200:203], v[40:43]
	v_mfma_f32_16x16x32_bf16 v[28:31], v[148:151], v[208:211], v[28:31]
	v_mfma_f32_16x16x32_bf16 v[24:27], v[168:171], v[208:211], v[24:27]
	v_mfma_f32_16x16x32_bf16 v[12:15], v[148:151], v[216:219], v[12:15]
	v_mfma_f32_16x16x32_bf16 v[8:11], v[168:171], v[216:219], v[8:11]
	v_mfma_f32_16x16x32_bf16 v[60:63], v[152:155], v[196:199], v[60:63]
	v_mfma_f32_16x16x32_bf16 v[56:59], v[172:175], v[196:199], v[56:59]
	v_mfma_f32_16x16x32_bf16 v[44:47], v[152:155], v[204:207], v[44:47]
	v_mfma_f32_16x16x32_bf16 v[40:43], v[172:175], v[204:207], v[40:43]
	v_mfma_f32_16x16x32_bf16 v[28:31], v[152:155], v[212:215], v[28:31]
	v_mfma_f32_16x16x32_bf16 v[24:27], v[172:175], v[212:215], v[24:27]
	v_mfma_f32_16x16x32_bf16 v[12:15], v[152:155], v[220:223], v[12:15]
	v_mfma_f32_16x16x32_bf16 v[8:11], v[172:175], v[220:223], v[8:11]
	s_setprio 0
	s_setprio 1
	v_mfma_f32_16x16x32_bf16 v[52:55], v[176:179], v[192:195], v[52:55]
	v_mfma_f32_16x16x32_bf16 v[48:51], v[184:187], v[192:195], v[48:51]
	v_mfma_f32_16x16x32_bf16 v[36:39], v[176:179], v[200:203], v[36:39]
	v_mfma_f32_16x16x32_bf16 v[32:35], v[184:187], v[200:203], v[32:35]
	v_mfma_f32_16x16x32_bf16 v[20:23], v[176:179], v[208:211], v[20:23]
	v_mfma_f32_16x16x32_bf16 v[16:19], v[184:187], v[208:211], v[16:19]
	v_mfma_f32_16x16x32_bf16 v[4:7], v[176:179], v[216:219], v[4:7]
	v_mfma_f32_16x16x32_bf16 v[0:3], v[184:187], v[216:219], v[0:3]
	s_barrier
	s_setprio 3
	v_mfma_f32_16x16x32_bf16 v[52:55], v[180:183], v[196:199], v[52:55]
	v_mfma_f32_16x16x32_bf16 v[48:51], v[188:191], v[196:199], v[48:51]
	v_mfma_f32_16x16x32_bf16 v[36:39], v[180:183], v[204:207], v[36:39]
	v_mfma_f32_16x16x32_bf16 v[32:35], v[188:191], v[204:207], v[32:35]
	v_mfma_f32_16x16x32_bf16 v[20:23], v[180:183], v[212:215], v[20:23]
	v_mfma_f32_16x16x32_bf16 v[16:19], v[188:191], v[212:215], v[16:19]
	v_mfma_f32_16x16x32_bf16 v[4:7], v[180:183], v[220:223], v[4:7]
	v_mfma_f32_16x16x32_bf16 v[0:3], v[188:191], v[220:223], v[0:3]
	s_setprio 0
	s_add_i32 s42, s42, 2
	s_add_u32 s8, s8, 0x100
	s_addc_u32 s9, s9, 0
	s_add_u32 s40, s40, 0x100
	s_addc_u32 s41, s41, 0
	s_cmp_gt_u32 s42, 29
	s_cbranch_scc0 .LBB0_393
	s_and_b64 vcc, exec, s[24:25]
	s_cbranch_vccz .LBB0_396
	s_barrier

; #define PG8_STAGE(bufoff, gbase, voff) do { _Pragma("unroll") for (int _i = 0; _i < 2; ++_i) \
;         __builtin_amdgcn_global_load_lds((const unsigned*)((const char*)(gbase) + (voff)[_i]), (PG8_LAS unsigned*)(lds + (bufoff) + ldsw + _i * 8192), 16, 0, 0); } while (0)
; #define PG8_LDA(dst, b, h) do { _Pragma("unroll") for (int m = 0; m < 4; ++m) _Pragma("unroll") for (int k = 0; k < 2; ++k) dst[m][k] = *(const PG8_LAS bf16x8*)(lds + PG8_SA(b, h) + aoff + m * 2048 + k * 1024); } while (0)
; #define PG8_LDB(dst, b, h) do { _Pragma("unroll") for (int n = 0; n < 2; ++n) _Pragma("unroll") for (int k = 0; k < 2; ++k) dst[n][k] = *(const PG8_LAS bf16x8*)(lds + PG8_SB(b, h) + boff + n * 2048 + k * 1024); } while (0)
; #define PG8_MMA(ai, bj, At, Bt) do { __builtin_amdgcn_s_setprio(1); _Pragma("unroll") for (int m = 0; m < 4; ++m) _Pragma("unroll") for (int n = 0; n < 2; ++n) _Pragma("unroll") for (int k = 0; k < 2; ++k) \
;         acc[ai][bj][m][n] = __builtin_amdgcn_mfma_f32_16x16x32_bf16(Bt[n][k], At[m][k], acc[ai][bj][m][n], 0, 0, 0); __builtin_amdgcn_s_setprio(0); } while (0)
; #define PG8_WAIT_V(n) asm volatile("s_waitcnt vmcnt(" #n ")" ::: "memory")
; #define PG8_WAIT_L(n) asm volatile("s_waitcnt lgkmcnt(" #n ")" ::: "memory")
; template <class Epi, class Sched, bool ALIGN_EPI = false, bool SP2 = false>
; __device__ __forceinline__ void gemm_phase(PG8_LAS unsigned char* lds, const Gemm g, const Sched& S, const Epi& E, int wave_in) {
;     ...
;             const bool last = (t == nt - 2);
;             const char* a1 = cA + (size_t)(t + 1) * kstep;
;             const char* a2 = last ? nA : cA + (size_t)(t + 2) * kstep; const char* b2 = last ? nB : cB + (size_t)(t + 2) * kstep;
;             const char* a3 = a2 + kstep; const char* b3 = b2 + kstep;
;             if (last && has_next) S.a_ready(nxt);
;             if constexpr (SP2) {
;             PG8_LDB(B0, 0, 0); PG8_LDB(B1, 0, 1); PG8_SCHED; PG8_LDA(At, 0, 0); PG8_STAGE(PG8_SA(1, 1), a1 + hstep, voffA);
;             PG8_WAIT_V(8); PG8_WAIT_L(0); PG8_BAR; PG8_MMA(0, 0, At, B0); PG8_MMA(0, 1, At, B1); PG8_BAR; PG8_SCHED;
;             PG8_LDA(At, 0, 1); PG8_STAGE(PG8_SB(0, 0), b2, voffB); PG8_STAGE(PG8_SB(0, 1), b2 + hstep, voffB); PG8_STAGE(PG8_SA(0, 0), a2, voffA);
;             PG8_WAIT_V(8); PG8_WAIT_L(0); PG8_BAR; PG8_MMA(1, 0, At, B0); PG8_MMA(1, 1, At, B1); PG8_BAR; PG8_SCHED;
.LBB0_845:
	ds_read_b128 v[140:143], v147
	ds_read_b128 v[152:155], v147 offset:1024
	ds_read_b128 v[156:159], v147 offset:2048
	ds_read_b128 v[160:163], v147 offset:3072
	ds_read_b128 v[164:167], v148
	ds_read_b128 v[168:171], v148 offset:1024
	ds_read_b128 v[172:175], v148 offset:2048
	ds_read_b128 v[176:179], v148 offset:3072
	s_add_u32 s26, s24, 0xfff80080
	s_addc_u32 s27, s25, -1
	s_cmp_eq_u32 s48, 28
	s_cselect_b32 s29, s15, s27
	s_cselect_b32 s28, s21, s26
	s_cselect_b32 s27, s13, s47
	s_cselect_b32 s26, s45, s46
	v_lshl_add_u64 v[212:213], s[24:25], 0, v[132:133]
	s_add_i32 m0, s23, 0xc000
	ds_read_b128 v[180:183], v149
	ds_read_b128 v[184:187], v149 offset:1024
	ds_read_b128 v[188:191], v149 offset:2048
	ds_read_b128 v[192:195], v149 offset:3072
	ds_read_b128 v[196:199], v149 offset:4096
	ds_read_b128 v[200:203], v149 offset:5120
	ds_read_b128 v[204:207], v149 offset:6144
	ds_read_b128 v[208:211], v149 offset:7168
	global_load_lds_dwordx4 v[212:213], off
	v_lshl_add_u64 v[212:213], s[24:25], 0, v[134:135]
	s_add_i32 m0, s23, 0xe000
	s_nop 0
	global_load_lds_dwordx4 v[212:213], off
	s_waitcnt vmcnt(8)
	s_waitcnt lgkmcnt(0)
	s_barrier
	s_setprio 1
	s_waitcnt lgkmcnt(0)
	v_mfma_f32_16x16x32_bf16 v[124:127], v[140:143], v[180:183], v[124:127]
	v_mfma_f32_16x16x32_bf16 v[120:123], v[156:159], v[180:183], v[120:123]
	v_mfma_f32_16x16x32_bf16 v[108:111], v[140:143], v[188:191], v[108:111]
	v_mfma_f32_16x16x32_bf16 v[104:107], v[156:159], v[188:191], v[104:107]
	v_mfma_f32_16x16x32_bf16 v[92:95], v[140:143], v[196:199], v[92:95]
	v_mfma_f32_16x16x32_bf16 v[88:91], v[156:159], v[196:199], v[88:91]
	v_mfma_f32_16x16x32_bf16 v[76:79], v[140:143], v[204:207], v[76:79]
	v_mfma_f32_16x16x32_bf16 v[72:75], v[156:159], v[204:207], v[72:75]
	v_mfma_f32_16x16x32_bf16 v[124:127], v[152:155], v[184:187], v[124:127]
	v_mfma_f32_16x16x32_bf16 v[120:123], v[160:163], v[184:187], v[120:123]
	v_mfma_f32_16x16x32_bf16 v[108:111], v[152:155], v[192:195], v[108:111]
	v_mfma_f32_16x16x32_bf16 v[104:107], v[160:163], v[192:195], v[104:107]
	v_mfma_f32_16x16x32_bf16 v[92:95], v[152:155], v[200:203], v[92:95]
	v_mfma_f32_16x16x32_bf16 v[88:91], v[160:163], v[200:203], v[88:91]
	v_mfma_f32_16x16x32_bf16 v[76:79], v[152:155], v[208:211], v[76:79]
	v_mfma_f32_16x16x32_bf16 v[72:75], v[160:163], v[208:211], v[72:75]
	s_setprio 0
	s_setprio 1
	v_mfma_f32_16x16x32_bf16 v[116:119], v[164:167], v[180:183], v[116:119]
	v_mfma_f32_16x16x32_bf16 v[112:115], v[172:175], v[180:183], v[112:115]
	v_mfma_f32_16x16x32_bf16 v[100:103], v[164:167], v[188:191], v[100:103]
	v_mfma_f32_16x16x32_bf16 v[96:99], v[172:175], v[188:191], v[96:99]
	v_mfma_f32_16x16x32_bf16 v[84:87], v[164:167], v[196:199], v[84:87]
	v_mfma_f32_16x16x32_bf16 v[80:83], v[172:175], v[196:199], v[80:83]
	v_mfma_f32_16x16x32_bf16 v[68:71], v[164:167], v[204:207], v[68:71]
	v_mfma_f32_16x16x32_bf16 v[64:67], v[172:175], v[204:207], v[64:67]
	s_barrier
	s_setprio 3
	v_mfma_f32_16x16x32_bf16 v[116:119], v[168:171], v[184:187], v[116:119]
	v_mfma_f32_16x16x32_bf16 v[112:115], v[176:179], v[184:187], v[112:115]
	v_mfma_f32_16x16x32_bf16 v[100:103], v[168:171], v[192:195], v[100:103]
	v_mfma_f32_16x16x32_bf16 v[96:99], v[176:179], v[192:195], v[96:99]
	v_mfma_f32_16x16x32_bf16 v[84:87], v[168:171], v[200:203], v[84:87]
	v_mfma_f32_16x16x32_bf16 v[80:83], v[176:179], v[200:203], v[80:83]
	v_mfma_f32_16x16x32_bf16 v[68:71], v[168:171], v[208:211], v[68:71]
	v_mfma_f32_16x16x32_bf16 v[64:67], v[176:179], v[208:211], v[64:67]
	s_setprio 0
	s_add_i32 s49, s43, s30
	v_lshl_add_u64 v[212:213], s[26:27], 0, v[128:129]
	s_mov_b32 m0, s49
	ds_read_b128 v[180:183], v149 offset:16384
	ds_read_b128 v[184:187], v149 offset:17408
	ds_read_b128 v[188:191], v149 offset:18432
	ds_read_b128 v[192:195], v149 offset:19456
	ds_read_b128 v[196:199], v149 offset:20480
	ds_read_b128 v[200:203], v149 offset:21504
	ds_read_b128 v[204:207], v149 offset:22528
	ds_read_b128 v[208:211], v149 offset:23552
	global_load_lds_dwordx4 v[212:213], off
	s_add_i32 m0, s49, 0x2000
	s_add_u32 s50, s26, 0x80000
	v_lshl_add_u64 v[214:215], s[26:27], 0, v[130:131]
	s_addc_u32 s51, s27, 0
	s_add_i32 s49, s44, s30
	global_load_lds_dwordx4 v[214:215], off
	v_lshl_add_u64 v[216:217], s[50:51], 0, v[128:129]
	s_mov_b32 m0, s49
	v_lshl_add_u64 v[218:219], s[28:29], 0, v[130:131]
	global_load_lds_dwordx4 v[216:217], off
	v_lshl_add_u64 v[216:217], s[50:51], 0, v[130:131]
	s_add_i32 m0, s49, 0x2000
	s_nop 0
	global_load_lds_dwordx4 v[216:217], off
	v_lshl_add_u64 v[216:217], s[28:29], 0, v[128:129]
	s_mov_b32 m0, s23
	s_nop 0
	global_load_lds_dwordx4 v[216:217], off
	s_mov_b32 m0, s34
	s_nop 0
	global_load_lds_dwordx4 v[218:219], off
	s_waitcnt vmcnt(8)
	s_waitcnt lgkmcnt(0)
	s_barrier
	s_setprio 1
	s_waitcnt lgkmcnt(0)
	v_mfma_f32_16x16x32_bf16 v[60:63], v[140:143], v[180:183], v[60:63]
	v_mfma_f32_16x16x32_bf16 v[56:59], v[156:159], v[180:183], v[56:59]
	v_mfma_f32_16x16x32_bf16 v[44:47], v[140:143], v[188:191], v[44:47]
	v_mfma_f32_16x16x32_bf16 v[40:43], v[156:159], v[188:191], v[40:43]
	v_mfma_f32_16x16x32_bf16 v[28:31], v[140:143], v[196:199], v[28:31]
	v_mfma_f32_16x16x32_bf16 v[24:27], v[156:159], v[196:199], v[24:27]
	v_mfma_f32_16x16x32_bf16 v[12:15], v[140:143], v[204:207], v[12:15]
	v_mfma_f32_16x16x32_bf16 v[8:11], v[156:159], v[204:207], v[8:11]
	v_mfma_f32_16x16x32_bf16 v[60:63], v[152:155], v[184:187], v[60:63]
	v_mfma_f32_16x16x32_bf16 v[56:59], v[160:163], v[184:187], v[56:59]
	v_mfma_f32_16x16x32_bf16 v[44:47], v[152:155], v[192:195], v[44:47]
	v_mfma_f32_16x16x32_bf16 v[40:43], v[160:163], v[192:195], v[40:43]
	v_mfma_f32_16x16x32_bf16 v[28:31], v[152:155], v[200:203], v[28:31]
	v_mfma_f32_16x16x32_bf16 v[24:27], v[160:163], v[200:203], v[24:27]
	v_mfma_f32_16x16x32_bf16 v[12:15], v[152:155], v[208:211], v[12:15]
	v_mfma_f32_16x16x32_bf16 v[8:11], v[160:163], v[208:211], v[8:11]
	s_setprio 0
	s_setprio 1
	v_mfma_f32_16x16x32_bf16 v[52:55], v[164:167], v[180:183], v[52:55]
	v_mfma_f32_16x16x32_bf16 v[48:51], v[172:175], v[180:183], v[48:51]
	v_mfma_f32_16x16x32_bf16 v[36:39], v[164:167], v[188:191], v[36:39]
	v_mfma_f32_16x16x32_bf16 v[32:35], v[172:175], v[188:191], v[32:35]
	v_mfma_f32_16x16x32_bf16 v[20:23], v[164:167], v[196:199], v[20:23]
	v_mfma_f32_16x16x32_bf16 v[16:19], v[172:175], v[196:199], v[16:19]
	v_mfma_f32_16x16x32_bf16 v[4:7], v[164:167], v[204:207], v[4:7]
	v_mfma_f32_16x16x32_bf16 v[0:3], v[172:175], v[204:207], v[0:3]
	s_barrier
; #define PG8_STAGE(bufoff, gbase, voff) do { _Pragma("unroll") for (int _i = 0; _i < 2; ++_i) \
;         __builtin_amdgcn_global_load_lds((const unsigned*)((const char*)(gbase) + (voff)[_i]), (PG8_LAS unsigned*)(lds + (bufoff) + ldsw + _i * 8192), 16, 0, 0); } while (0)
; #define PG8_LDA(dst, b, h) do { _Pragma("unroll") for (int m = 0; m < 4; ++m) _Pragma("unroll") for (int k = 0; k < 2; ++k) dst[m][k] = *(const PG8_LAS bf16x8*)(lds + PG8_SA(b, h) + aoff + m * 2048 + k * 1024); } while (0)
; #define PG8_LDB(dst, b, h) do { _Pragma("unroll") for (int n = 0; n < 2; ++n) _Pragma("unroll") for (int k = 0; k < 2; ++k) dst[n][k] = *(const PG8_LAS bf16x8*)(lds + PG8_SB(b, h) + boff + n * 2048 + k * 1024); } while (0)
; #define PG8_MMA(ai, bj, At, Bt) do { __builtin_amdgcn_s_setprio(1); _Pragma("unroll") for (int m = 0; m < 4; ++m) _Pragma("unroll") for (int n = 0; n < 2; ++n) _Pragma("unroll") for (int k = 0; k < 2; ++k) \
;         acc[ai][bj][m][n] = __builtin_amdgcn_mfma_f32_16x16x32_bf16(Bt[n][k], At[m][k], acc[ai][bj][m][n], 0, 0, 0); __builtin_amdgcn_s_setprio(0); } while (0)
; #define PG8_WAIT_V(n) asm volatile("s_waitcnt vmcnt(" #n ")" ::: "memory")
; #define PG8_WAIT_L(n) asm volatile("s_waitcnt lgkmcnt(" #n ")" ::: "memory")
; #define PG8_BAR __builtin_amdgcn_s_barrier()
; #define PG8_SCHED __builtin_amdgcn_sched_barrier(0)
; template <class Epi, class Sched, bool ALIGN_EPI = false, bool SP2 = false>
; __device__ __forceinline__ void gemm_phase(PG8_LAS unsigned char* lds, const Gemm g, const Sched& S, const Epi& E, int wave_in) {
;     ...
;             PG8_LDB(B0, 1, 0); PG8_LDB(B1, 1, 1); PG8_SCHED; PG8_LDA(At, 1, 0); PG8_STAGE(PG8_SA(0, 1), a2 + hstep, voffA);
;             PG8_WAIT_V(8); PG8_WAIT_L(0); PG8_BAR; PG8_MMA(0, 0, At, B0); PG8_MMA(0, 1, At, B1); PG8_BAR; PG8_SCHED;
;             PG8_LDA(At, 1, 1); PG8_STAGE(PG8_SB(1, 0), b3, voffB); PG8_STAGE(PG8_SB(1, 1), b3 + hstep, voffB); PG8_STAGE(PG8_SA(1, 0), a3, voffA);
	s_setprio 3
	v_mfma_f32_16x16x32_bf16 v[52:55], v[168:171], v[184:187], v[52:55]
	v_mfma_f32_16x16x32_bf16 v[48:51], v[176:179], v[184:187], v[48:51]
	v_mfma_f32_16x16x32_bf16 v[36:39], v[168:171], v[192:195], v[36:39]
	v_mfma_f32_16x16x32_bf16 v[32:35], v[176:179], v[192:195], v[32:35]
	v_mfma_f32_16x16x32_bf16 v[20:23], v[168:171], v[200:203], v[20:23]
	v_mfma_f32_16x16x32_bf16 v[16:19], v[176:179], v[200:203], v[16:19]
	v_mfma_f32_16x16x32_bf16 v[4:7], v[168:171], v[208:211], v[4:7]
	v_mfma_f32_16x16x32_bf16 v[0:3], v[176:179], v[208:211], v[0:3]
	s_setprio 0
	s_add_i32 s49, 0, 0x18000
	v_add_u32_e32 v151, s49, v145
	s_add_i32 s50, 0, 0x1c000
	ds_read_b128 v[140:143], v151
	ds_read_b128 v[152:155], v151 offset:1024
	ds_read_b128 v[156:159], v151 offset:2048
	ds_read_b128 v[160:163], v151 offset:3072
	v_add_u32_e32 v151, s50, v145
	ds_read_b128 v[164:167], v151
	ds_read_b128 v[168:171], v151 offset:1024
	ds_read_b128 v[172:175], v151 offset:2048
	ds_read_b128 v[176:179], v151 offset:3072
	s_add_u32 s28, s28, 0x80000
	s_addc_u32 s29, s29, 0
	s_mov_b32 m0, s35
	v_lshl_add_u64 v[220:221], s[28:29], 0, v[128:129]
	ds_read_b128 v[180:183], v149 offset:32768
	ds_read_b128 v[184:187], v149 offset:33792
	ds_read_b128 v[188:191], v149 offset:34816
	ds_read_b128 v[192:195], v149 offset:35840
	ds_read_b128 v[196:199], v149 offset:36864
	ds_read_b128 v[200:203], v149 offset:37888
	ds_read_b128 v[204:207], v149 offset:38912
	ds_read_b128 v[208:211], v149 offset:39936
	global_load_lds_dwordx4 v[220:221], off
	v_lshl_add_u64 v[220:221], s[28:29], 0, v[130:131]
	s_mov_b32 m0, s36
	s_nop 0
	global_load_lds_dwordx4 v[220:221], off
	s_waitcnt vmcnt(8)
	s_waitcnt lgkmcnt(0)
	s_barrier
	s_setprio 1
	s_waitcnt lgkmcnt(0)
	v_mfma_f32_16x16x32_bf16 v[124:127], v[140:143], v[180:183], v[124:127]
	v_mfma_f32_16x16x32_bf16 v[120:123], v[156:159], v[180:183], v[120:123]
	v_mfma_f32_16x16x32_bf16 v[108:111], v[140:143], v[188:191], v[108:111]
	v_mfma_f32_16x16x32_bf16 v[104:107], v[156:159], v[188:191], v[104:107]
	v_mfma_f32_16x16x32_bf16 v[92:95], v[140:143], v[196:199], v[92:95]
	v_mfma_f32_16x16x32_bf16 v[88:91], v[156:159], v[196:199], v[88:91]
	v_mfma_f32_16x16x32_bf16 v[76:79], v[140:143], v[204:207], v[76:79]
	v_mfma_f32_16x16x32_bf16 v[72:75], v[156:159], v[204:207], v[72:75]
	v_mfma_f32_16x16x32_bf16 v[124:127], v[152:155], v[184:187], v[124:127]
	v_mfma_f32_16x16x32_bf16 v[120:123], v[160:163], v[184:187], v[120:123]
	v_mfma_f32_16x16x32_bf16 v[108:111], v[152:155], v[192:195], v[108:111]
	v_mfma_f32_16x16x32_bf16 v[104:107], v[160:163], v[192:195], v[104:107]
	v_mfma_f32_16x16x32_bf16 v[92:95], v[152:155], v[200:203], v[92:95]
	v_mfma_f32_16x16x32_bf16 v[88:91], v[160:163], v[200:203], v[88:91]
	v_mfma_f32_16x16x32_bf16 v[76:79], v[152:155], v[208:211], v[76:79]
	v_mfma_f32_16x16x32_bf16 v[72:75], v[160:163], v[208:211], v[72:75]
	s_setprio 0
	s_setprio 1
	v_mfma_f32_16x16x32_bf16 v[116:119], v[164:167], v[180:183], v[116:119]
	v_mfma_f32_16x16x32_bf16 v[112:115], v[172:175], v[180:183], v[112:115]
	v_mfma_f32_16x16x32_bf16 v[100:103], v[164:167], v[188:191], v[100:103]
	v_mfma_f32_16x16x32_bf16 v[96:99], v[172:175], v[188:191], v[96:99]
	v_mfma_f32_16x16x32_bf16 v[84:87], v[164:167], v[196:199], v[84:87]
	v_mfma_f32_16x16x32_bf16 v[80:83], v[172:175], v[196:199], v[80:83]
	v_mfma_f32_16x16x32_bf16 v[68:71], v[164:167], v[204:207], v[68:71]
	v_mfma_f32_16x16x32_bf16 v[64:67], v[172:175], v[204:207], v[64:67]
	s_barrier
	s_setprio 3
	v_mfma_f32_16x16x32_bf16 v[116:119], v[168:171], v[184:187], v[116:119]
	v_mfma_f32_16x16x32_bf16 v[112:115], v[176:179], v[184:187], v[112:115]
	v_mfma_f32_16x16x32_bf16 v[100:103], v[168:171], v[192:195], v[100:103]
	v_mfma_f32_16x16x32_bf16 v[96:99], v[176:179], v[192:195], v[96:99]
	v_mfma_f32_16x16x32_bf16 v[84:87], v[168:171], v[200:203], v[84:87]
	v_mfma_f32_16x16x32_bf16 v[80:83], v[176:179], v[200:203], v[80:83]
	v_mfma_f32_16x16x32_bf16 v[68:71], v[168:171], v[208:211], v[68:71]
	v_mfma_f32_16x16x32_bf16 v[64:67], v[176:179], v[208:211], v[64:67]
	s_setprio 0
	s_add_i32 s28, s49, s30
	v_lshl_add_u64 v[212:213], v[212:213], 0, s[2:3]
	s_mov_b32 m0, s28
	ds_read_b128 v[180:183], v149 offset:49152
	ds_read_b128 v[184:187], v149 offset:50176
	ds_read_b128 v[188:191], v149 offset:51200
	ds_read_b128 v[192:195], v149 offset:52224
	ds_read_b128 v[196:199], v149 offset:53248
	ds_read_b128 v[200:203], v149 offset:54272
	ds_read_b128 v[204:207], v149 offset:55296
	ds_read_b128 v[208:211], v149 offset:56320
	global_load_lds_dwordx4 v[212:213], off
	s_add_i32 m0, s28, 0x2000
	s_add_u32 s26, s26, 0x80080
	v_lshl_add_u64 v[212:213], v[214:215], 0, s[2:3]
	s_addc_u32 s27, s27, 0
	s_add_i32 s28, s50, s30
	global_load_lds_dwordx4 v[212:213], off
	v_lshl_add_u64 v[212:213], s[26:27], 0, v[128:129]
	s_mov_b32 m0, s28
	s_nop 0
	global_load_lds_dwordx4 v[212:213], off
	v_lshl_add_u64 v[212:213], s[26:27], 0, v[130:131]
	s_add_i32 m0, s28, 0x2000
	s_nop 0
	global_load_lds_dwordx4 v[212:213], off
	v_lshl_add_u64 v[212:213], v[216:217], 0, s[2:3]
	s_mov_b32 m0, s38
	s_nop 0
	global_load_lds_dwordx4 v[212:213], off
	v_lshl_add_u64 v[212:213], v[218:219], 0, s[2:3]
	s_mov_b32 m0, s39
	s_nop 0
	global_load_lds_dwordx4 v[212:213], off
	s_waitcnt vmcnt(8)
	s_waitcnt lgkmcnt(0)
	s_barrier
; #define PG8_STAGE(bufoff, gbase, voff) do { _Pragma("unroll") for (int _i = 0; _i < 2; ++_i) \
;         __builtin_amdgcn_global_load_lds((const unsigned*)((const char*)(gbase) + (voff)[_i]), (PG8_LAS unsigned*)(lds + (bufoff) + ldsw + _i * 8192), 16, 0, 0); } while (0)
; #define PG8_LDA(dst, b, h) do { _Pragma("unroll") for (int m = 0; m < 4; ++m) _Pragma("unroll") for (int k = 0; k < 2; ++k) dst[m][k] = *(const PG8_LAS bf16x8*)(lds + PG8_SA(b, h) + aoff + m * 2048 + k * 1024); } while (0)
; #define PG8_MMA(ai, bj, At, Bt) do { __builtin_amdgcn_s_setprio(1); _Pragma("unroll") for (int m = 0; m < 4; ++m) _Pragma("unroll") for (int n = 0; n < 2; ++n) _Pragma("unroll") for (int k = 0; k < 2; ++k) \
;         acc[ai][bj][m][n] = __builtin_amdgcn_mfma_f32_16x16x32_bf16(Bt[n][k], At[m][k], acc[ai][bj][m][n], 0, 0, 0); __builtin_amdgcn_s_setprio(0); } while (0)
; #define PG8_WAIT_V(n) asm volatile("s_waitcnt vmcnt(" #n ")" ::: "memory")
; #define PG8_WAIT_L(n) asm volatile("s_waitcnt lgkmcnt(" #n ")" ::: "memory")
; #define PG8_BAR __builtin_amdgcn_s_barrier()
; #define PG8_SCHED __builtin_amdgcn_sched_barrier(0)
;     __device__ __forceinline__ void operator()(const f32x4 (&acc)[2][2][4][2], const Unit& u, int wr, int wc, int fr, int fq) const {
;     ...
;             for (int m = 0; m < 4; ++m) { const int row = u.pm * BM + ai * HALF + wr * 64 + m * 16 + fr; const size_t off = (size_t)row * ldc + col0;
;                 float ss = 0.f;
; #pragma unroll
;                 for (int bj = 0; bj < 2; ++bj)
; #pragma unroll
;                     for (int n = 0; n < 2; ++n) { f32x4 bs;
;                         if (BASE_BF16) { const u32x2 t = *(const u32x2*)((const bf16_t*)base + off + bj * HALF + n * 16);
; template <class Epi, class Sched, bool ALIGN_EPI = false, bool SP2 = false>
; __device__ __forceinline__ void gemm_phase(PG8_LAS unsigned char* lds, const Gemm g, const Sched& S, const Epi& E, int wave_in) {
;     ...
;             PG8_LDA(At, 1, 1); PG8_STAGE(PG8_SB(1, 0), b3, voffB); PG8_STAGE(PG8_SB(1, 1), b3 + hstep, voffB); PG8_STAGE(PG8_SA(1, 0), a3, voffA);
;             PG8_WAIT_V(8); PG8_WAIT_L(0); PG8_BAR; PG8_MMA(1, 0, At, B0); PG8_MMA(1, 1, At, B1); PG8_BAR; PG8_SCHED;
	s_setprio 1
	s_waitcnt lgkmcnt(0)
	v_mfma_f32_16x16x32_bf16 v[60:63], v[140:143], v[180:183], v[60:63]
	v_mfma_f32_16x16x32_bf16 v[56:59], v[156:159], v[180:183], v[56:59]
	v_mfma_f32_16x16x32_bf16 v[44:47], v[140:143], v[188:191], v[44:47]
	v_mfma_f32_16x16x32_bf16 v[40:43], v[156:159], v[188:191], v[40:43]
	v_mfma_f32_16x16x32_bf16 v[28:31], v[140:143], v[196:199], v[28:31]
	v_mfma_f32_16x16x32_bf16 v[24:27], v[156:159], v[196:199], v[24:27]
	v_mfma_f32_16x16x32_bf16 v[12:15], v[140:143], v[204:207], v[12:15]
	v_mfma_f32_16x16x32_bf16 v[8:11], v[156:159], v[204:207], v[8:11]
	v_mfma_f32_16x16x32_bf16 v[60:63], v[152:155], v[184:187], v[60:63]
	v_mfma_f32_16x16x32_bf16 v[56:59], v[160:163], v[184:187], v[56:59]
	v_mfma_f32_16x16x32_bf16 v[44:47], v[152:155], v[192:195], v[44:47]
	v_mfma_f32_16x16x32_bf16 v[40:43], v[160:163], v[192:195], v[40:43]
	v_mfma_f32_16x16x32_bf16 v[28:31], v[152:155], v[200:203], v[28:31]
	v_mfma_f32_16x16x32_bf16 v[24:27], v[160:163], v[200:203], v[24:27]
	v_mfma_f32_16x16x32_bf16 v[12:15], v[152:155], v[208:211], v[12:15]
	v_mfma_f32_16x16x32_bf16 v[8:11], v[160:163], v[208:211], v[8:11]
	s_setprio 0
	s_setprio 1
	v_mfma_f32_16x16x32_bf16 v[52:55], v[164:167], v[180:183], v[52:55]
	v_mfma_f32_16x16x32_bf16 v[48:51], v[172:175], v[180:183], v[48:51]
	v_mfma_f32_16x16x32_bf16 v[36:39], v[164:167], v[188:191], v[36:39]
	v_mfma_f32_16x16x32_bf16 v[32:35], v[172:175], v[188:191], v[32:35]
	v_mfma_f32_16x16x32_bf16 v[20:23], v[164:167], v[196:199], v[20:23]
	v_mfma_f32_16x16x32_bf16 v[16:19], v[172:175], v[196:199], v[16:19]
	v_mfma_f32_16x16x32_bf16 v[4:7], v[164:167], v[204:207], v[4:7]
	v_mfma_f32_16x16x32_bf16 v[0:3], v[172:175], v[204:207], v[0:3]
	s_barrier
	s_setprio 3
	v_mfma_f32_16x16x32_bf16 v[52:55], v[168:171], v[184:187], v[52:55]
	v_mfma_f32_16x16x32_bf16 v[48:51], v[176:179], v[184:187], v[48:51]
	v_mfma_f32_16x16x32_bf16 v[36:39], v[168:171], v[192:195], v[36:39]
	v_mfma_f32_16x16x32_bf16 v[32:35], v[176:179], v[192:195], v[32:35]
	v_mfma_f32_16x16x32_bf16 v[20:23], v[168:171], v[200:203], v[20:23]
	v_mfma_f32_16x16x32_bf16 v[16:19], v[176:179], v[200:203], v[16:19]
	v_mfma_f32_16x16x32_bf16 v[4:7], v[168:171], v[208:211], v[4:7]
	v_mfma_f32_16x16x32_bf16 v[0:3], v[176:179], v[208:211], v[0:3]
	s_setprio 0
	s_add_i32 s48, s48, 2
	s_add_u32 s24, s24, 0x100
	s_addc_u32 s25, s25, 0
	s_add_u32 s46, s46, 0x100
	s_addc_u32 s47, s47, 0
	s_cmp_gt_u32 s48, 29
	s_cbranch_scc0 .LBB0_845
	v_lshl_add_u32 v142, s20, 8, v144
	v_lshl_or_b32 v140, s22, 8, v146
	v_lshlrev_b32_e32 v143, 12, v142
	v_lshl_add_u32 v143, v140, 1, v143
	v_lshlrev_b32_e32 v142, 2, v142
	v_xor_b32_e32 v151, 16, v150
	v_xor_b32_e32 v141, 32, v150
	v_lshlrev_b32_e32 v151, 2, v151
	v_lshlrev_b32_e32 v141, 2, v141
	v_mov_b32_e32 v140, v143
	global_load_dwordx2 v[152:153], v140, s[76:77]
	global_load_dwordx2 v[154:155], v140, s[76:77] offset:32
	global_load_dwordx2 v[156:157], v140, s[76:77] offset:256
	global_load_dwordx2 v[158:159], v140, s[76:77] offset:288
	v_add_u32_e32 v140, 0x10000, v143
	global_load_dwordx2 v[160:161], v140, s[76:77]
	global_load_dwordx2 v[162:163], v140, s[76:77] offset:32
	global_load_dwordx2 v[164:165], v140, s[76:77] offset:256
	global_load_dwordx2 v[166:167], v140, s[76:77] offset:288
	v_add_u32_e32 v140, 0x20000, v143
	global_load_dwordx2 v[168:169], v140, s[76:77]
	global_load_dwordx2 v[170:171], v140, s[76:77] offset:32
	global_load_dwordx2 v[172:173], v140, s[76:77] offset:256
	global_load_dwordx2 v[174:175], v140, s[76:77] offset:288
	v_add_u32_e32 v140, 0x30000, v143
	global_load_dwordx2 v[176:177], v140, s[76:77]
	global_load_dwordx2 v[178:179], v140, s[76:77] offset:32
	global_load_dwordx2 v[180:181], v140, s[76:77] offset:256
	global_load_dwordx2 v[182:183], v140, s[76:77] offset:288
	v_add_u32_e32 v140, 0x80000, v143
	global_load_dwordx2 v[184:185], v140, s[76:77]
	global_load_dwordx2 v[186:187], v140, s[76:77] offset:32
	global_load_dwordx2 v[188:189], v140, s[76:77] offset:256
	global_load_dwordx2 v[190:191], v140, s[76:77] offset:288
	v_add_u32_e32 v140, 0x90000, v143
	global_load_dwordx2 v[192:193], v140, s[76:77]
	global_load_dwordx2 v[194:195], v140, s[76:77] offset:32
	global_load_dwordx2 v[196:197], v140, s[76:77] offset:256
	global_load_dwordx2 v[198:199], v140, s[76:77] offset:288
	v_add_u32_e32 v140, 0xa0000, v143
	global_load_dwordx2 v[200:201], v140, s[76:77]
	global_load_dwordx2 v[202:203], v140, s[76:77] offset:32
	global_load_dwordx2 v[204:205], v140, s[76:77] offset:256
	global_load_dwordx2 v[206:207], v140, s[76:77] offset:288
	s_and_b64 vcc, exec, s[4:5]
	s_cbranch_vccz .LBB0_848
	s_barrier

; #define PG8_STAGE(bufoff, gbase, voff) do { _Pragma("unroll") for (int _i = 0; _i < 2; ++_i) \
;         __builtin_amdgcn_global_load_lds((const unsigned*)((const char*)(gbase) + (voff)[_i]), (PG8_LAS unsigned*)(lds + (bufoff) + ldsw + _i * 8192), 16, 0, 0); } while (0)
; #define PG8_LDA(dst, b, h) do { _Pragma("unroll") for (int m = 0; m < 4; ++m) _Pragma("unroll") for (int k = 0; k < 2; ++k) dst[m][k] = *(const PG8_LAS bf16x8*)(lds + PG8_SA(b, h) + aoff + m * 2048 + k * 1024); } while (0)
; #define PG8_LDB(dst, b, h) do { _Pragma("unroll") for (int n = 0; n < 2; ++n) _Pragma("unroll") for (int k = 0; k < 2; ++k) dst[n][k] = *(const PG8_LAS bf16x8*)(lds + PG8_SB(b, h) + boff + n * 2048 + k * 1024); } while (0)
; #define PG8_MMA(ai, bj, At, Bt) do { __builtin_amdgcn_s_setprio(1); _Pragma("unroll") for (int m = 0; m < 4; ++m) _Pragma("unroll") for (int n = 0; n < 2; ++n) _Pragma("unroll") for (int k = 0; k < 2; ++k) \
;         acc[ai][bj][m][n] = __builtin_amdgcn_mfma_f32_16x16x32_bf16(Bt[n][k], At[m][k], acc[ai][bj][m][n], 0, 0, 0); __builtin_amdgcn_s_setprio(0); } while (0)
; #define PG8_WAIT_V(n) asm volatile("s_waitcnt vmcnt(" #n ")" ::: "memory")
; #define PG8_WAIT_L(n) asm volatile("s_waitcnt lgkmcnt(" #n ")" ::: "memory")
; template <class Epi, class Sched, bool ALIGN_EPI = false, bool SP2 = false>
; __device__ __forceinline__ void gemm_phase(PG8_LAS unsigned char* lds, const Gemm g, const Sched& S, const Epi& E, int wave_in) {
;     ...
;             const bool last = (t == nt - 2);
;             const char* a1 = cA + (size_t)(t + 1) * kstep;
;             const char* a2 = last ? nA : cA + (size_t)(t + 2) * kstep; const char* b2 = last ? nB : cB + (size_t)(t + 2) * kstep;
;             const char* a3 = a2 + kstep; const char* b3 = b2 + kstep;
;             if (last && has_next) S.a_ready(nxt);
;             if constexpr (SP2) {
;             PG8_LDB(B0, 0, 0); PG8_LDB(B1, 0, 1); PG8_SCHED; PG8_LDA(At, 0, 0); PG8_STAGE(PG8_SA(1, 1), a1 + hstep, voffA);
;             PG8_WAIT_V(8); PG8_WAIT_L(0); PG8_BAR; PG8_MMA(0, 0, At, B0); PG8_MMA(0, 1, At, B1); PG8_BAR; PG8_SCHED;
;             PG8_LDA(At, 0, 1); PG8_STAGE(PG8_SB(0, 0), b2, voffB); PG8_STAGE(PG8_SB(0, 1), b2 + hstep, voffB); PG8_STAGE(PG8_SA(0, 0), a2, voffA);
;             PG8_WAIT_V(8); PG8_WAIT_L(0); PG8_BAR; PG8_MMA(1, 0, At, B0); PG8_MMA(1, 1, At, B1); PG8_BAR; PG8_SCHED;
.LBB0_929:
	ds_read_b128 v[144:147], v153
	ds_read_b128 v[158:161], v153 offset:1024
	ds_read_b128 v[162:165], v153 offset:2048
	ds_read_b128 v[166:169], v153 offset:3072
	ds_read_b128 v[170:173], v154
	ds_read_b128 v[174:177], v154 offset:1024
	ds_read_b128 v[178:181], v154 offset:2048
	ds_read_b128 v[182:185], v154 offset:3072
	s_add_u32 s22, s20, 0xfff80080
	s_addc_u32 s23, s21, -1
	s_cmp_eq_u32 s49, 28
	s_cselect_b32 s25, s15, s23
	s_cselect_b32 s24, s45, s22
	s_cselect_b32 s23, s13, s48
	s_cselect_b32 s22, s46, s47
	v_lshl_add_u64 v[148:149], s[20:21], 0, v[136:137]
	s_add_i32 m0, s31, 0xc000
	ds_read_b128 v[186:189], v155
	ds_read_b128 v[190:193], v155 offset:1024
	ds_read_b128 v[194:197], v155 offset:2048
	ds_read_b128 v[198:201], v155 offset:3072
	ds_read_b128 v[202:205], v155 offset:4096
	ds_read_b128 v[206:209], v155 offset:5120
	ds_read_b128 v[210:213], v155 offset:6144
	ds_read_b128 v[214:217], v155 offset:7168
	global_load_lds_dwordx4 v[148:149], off
	v_lshl_add_u64 v[148:149], s[20:21], 0, v[138:139]
	s_add_i32 m0, s31, 0xe000
	s_nop 0
	global_load_lds_dwordx4 v[148:149], off
	s_waitcnt vmcnt(8)
	s_waitcnt lgkmcnt(0)
	s_barrier
	s_setprio 1
	s_waitcnt lgkmcnt(0)
	v_mfma_f32_16x16x32_bf16 v[116:119], v[144:147], v[186:189], v[116:119]
	v_mfma_f32_16x16x32_bf16 v[112:115], v[162:165], v[186:189], v[112:115]
	v_mfma_f32_16x16x32_bf16 v[100:103], v[144:147], v[194:197], v[100:103]
	v_mfma_f32_16x16x32_bf16 v[96:99], v[162:165], v[194:197], v[96:99]
	v_mfma_f32_16x16x32_bf16 v[84:87], v[144:147], v[202:205], v[84:87]
	v_mfma_f32_16x16x32_bf16 v[80:83], v[162:165], v[202:205], v[80:83]
	v_mfma_f32_16x16x32_bf16 v[72:75], v[144:147], v[210:213], v[72:75]
	v_mfma_f32_16x16x32_bf16 v[64:67], v[162:165], v[210:213], v[64:67]
	v_mfma_f32_16x16x32_bf16 v[116:119], v[158:161], v[190:193], v[116:119]
	v_mfma_f32_16x16x32_bf16 v[112:115], v[166:169], v[190:193], v[112:115]
	v_mfma_f32_16x16x32_bf16 v[100:103], v[158:161], v[198:201], v[100:103]
	v_mfma_f32_16x16x32_bf16 v[96:99], v[166:169], v[198:201], v[96:99]
	v_mfma_f32_16x16x32_bf16 v[84:87], v[158:161], v[206:209], v[84:87]
	v_mfma_f32_16x16x32_bf16 v[80:83], v[166:169], v[206:209], v[80:83]
	v_mfma_f32_16x16x32_bf16 v[72:75], v[158:161], v[214:217], v[72:75]
	v_mfma_f32_16x16x32_bf16 v[64:67], v[166:169], v[214:217], v[64:67]
	s_setprio 0
	s_setprio 1
	v_mfma_f32_16x16x32_bf16 v[124:127], v[170:173], v[186:189], v[124:127]
	v_mfma_f32_16x16x32_bf16 v[120:123], v[178:181], v[186:189], v[120:123]
	v_mfma_f32_16x16x32_bf16 v[108:111], v[170:173], v[194:197], v[108:111]
	v_mfma_f32_16x16x32_bf16 v[104:107], v[178:181], v[194:197], v[104:107]
	v_mfma_f32_16x16x32_bf16 v[92:95], v[170:173], v[202:205], v[92:95]
	v_mfma_f32_16x16x32_bf16 v[88:91], v[178:181], v[202:205], v[88:91]
	v_mfma_f32_16x16x32_bf16 v[76:79], v[170:173], v[210:213], v[76:79]
	v_mfma_f32_16x16x32_bf16 v[68:71], v[178:181], v[210:213], v[68:71]
	s_barrier
	s_setprio 3
	v_mfma_f32_16x16x32_bf16 v[124:127], v[174:177], v[190:193], v[124:127]
	v_mfma_f32_16x16x32_bf16 v[120:123], v[182:185], v[190:193], v[120:123]
	v_mfma_f32_16x16x32_bf16 v[108:111], v[174:177], v[198:201], v[108:111]
	v_mfma_f32_16x16x32_bf16 v[104:107], v[182:185], v[198:201], v[104:107]
	v_mfma_f32_16x16x32_bf16 v[92:95], v[174:177], v[206:209], v[92:95]
	v_mfma_f32_16x16x32_bf16 v[88:91], v[182:185], v[206:209], v[88:91]
	v_mfma_f32_16x16x32_bf16 v[76:79], v[174:177], v[214:217], v[76:79]
	v_mfma_f32_16x16x32_bf16 v[68:71], v[182:185], v[214:217], v[68:71]
	s_setprio 0
	s_add_i32 s50, s41, s26
	v_lshl_add_u64 v[148:149], s[22:23], 0, v[132:133]
	s_mov_b32 m0, s50
	ds_read_b128 v[186:189], v155 offset:16384
	ds_read_b128 v[190:193], v155 offset:17408
	ds_read_b128 v[194:197], v155 offset:18432
	ds_read_b128 v[198:201], v155 offset:19456
	ds_read_b128 v[202:205], v155 offset:20480
	ds_read_b128 v[206:209], v155 offset:21504
	ds_read_b128 v[210:213], v155 offset:22528
	ds_read_b128 v[214:217], v155 offset:23552
	global_load_lds_dwordx4 v[148:149], off
	s_add_i32 m0, s50, 0x2000
	s_add_u32 s50, s22, 0x80000
	v_lshl_add_u64 v[218:219], s[22:23], 0, v[128:129]
	s_addc_u32 s51, s23, 0
	s_add_i32 s52, s42, s26
	global_load_lds_dwordx4 v[218:219], off
	v_lshl_add_u64 v[220:221], s[50:51], 0, v[132:133]
	s_mov_b32 m0, s52
	v_lshl_add_u64 v[222:223], s[24:25], 0, v[130:131]
	global_load_lds_dwordx4 v[220:221], off
	v_lshl_add_u64 v[220:221], s[50:51], 0, v[128:129]
	s_add_i32 m0, s52, 0x2000
	s_nop 0
	global_load_lds_dwordx4 v[220:221], off
	v_lshl_add_u64 v[220:221], s[24:25], 0, v[134:135]
	s_mov_b32 m0, s31
	s_nop 0
	global_load_lds_dwordx4 v[220:221], off
	s_mov_b32 m0, s33
	s_nop 0
	global_load_lds_dwordx4 v[222:223], off
	s_waitcnt vmcnt(8)
	s_waitcnt lgkmcnt(0)
	s_barrier
	s_setprio 1
	s_waitcnt lgkmcnt(0)
	v_mfma_f32_16x16x32_bf16 v[52:55], v[144:147], v[186:189], v[52:55]
	v_mfma_f32_16x16x32_bf16 v[48:51], v[162:165], v[186:189], v[48:51]
	v_mfma_f32_16x16x32_bf16 v[36:39], v[144:147], v[194:197], v[36:39]
	v_mfma_f32_16x16x32_bf16 v[32:35], v[162:165], v[194:197], v[32:35]
	v_mfma_f32_16x16x32_bf16 v[20:23], v[144:147], v[202:205], v[20:23]
	v_mfma_f32_16x16x32_bf16 v[16:19], v[162:165], v[202:205], v[16:19]
	v_mfma_f32_16x16x32_bf16 v[4:7], v[144:147], v[210:213], v[4:7]
	v_mfma_f32_16x16x32_bf16 v[0:3], v[162:165], v[210:213], v[0:3]
	v_mfma_f32_16x16x32_bf16 v[52:55], v[158:161], v[190:193], v[52:55]
	v_mfma_f32_16x16x32_bf16 v[48:51], v[166:169], v[190:193], v[48:51]
	v_mfma_f32_16x16x32_bf16 v[36:39], v[158:161], v[198:201], v[36:39]
	v_mfma_f32_16x16x32_bf16 v[32:35], v[166:169], v[198:201], v[32:35]
	v_mfma_f32_16x16x32_bf16 v[20:23], v[158:161], v[206:209], v[20:23]
	v_mfma_f32_16x16x32_bf16 v[16:19], v[166:169], v[206:209], v[16:19]
	v_mfma_f32_16x16x32_bf16 v[4:7], v[158:161], v[214:217], v[4:7]
	v_mfma_f32_16x16x32_bf16 v[0:3], v[166:169], v[214:217], v[0:3]
	s_setprio 0
	s_setprio 1
	v_mfma_f32_16x16x32_bf16 v[60:63], v[170:173], v[186:189], v[60:63]
	v_mfma_f32_16x16x32_bf16 v[56:59], v[178:181], v[186:189], v[56:59]
	v_mfma_f32_16x16x32_bf16 v[44:47], v[170:173], v[194:197], v[44:47]
	v_mfma_f32_16x16x32_bf16 v[40:43], v[178:181], v[194:197], v[40:43]
	v_mfma_f32_16x16x32_bf16 v[28:31], v[170:173], v[202:205], v[28:31]
	v_mfma_f32_16x16x32_bf16 v[24:27], v[178:181], v[202:205], v[24:27]
	v_mfma_f32_16x16x32_bf16 v[12:15], v[170:173], v[210:213], v[12:15]
	v_mfma_f32_16x16x32_bf16 v[8:11], v[178:181], v[210:213], v[8:11]
	s_barrier
; #define PG8_STAGE(bufoff, gbase, voff) do { _Pragma("unroll") for (int _i = 0; _i < 2; ++_i) \
;         __builtin_amdgcn_global_load_lds((const unsigned*)((const char*)(gbase) + (voff)[_i]), (PG8_LAS unsigned*)(lds + (bufoff) + ldsw + _i * 8192), 16, 0, 0); } while (0)
; #define PG8_LDA(dst, b, h) do { _Pragma("unroll") for (int m = 0; m < 4; ++m) _Pragma("unroll") for (int k = 0; k < 2; ++k) dst[m][k] = *(const PG8_LAS bf16x8*)(lds + PG8_SA(b, h) + aoff + m * 2048 + k * 1024); } while (0)
; #define PG8_LDB(dst, b, h) do { _Pragma("unroll") for (int n = 0; n < 2; ++n) _Pragma("unroll") for (int k = 0; k < 2; ++k) dst[n][k] = *(const PG8_LAS bf16x8*)(lds + PG8_SB(b, h) + boff + n * 2048 + k * 1024); } while (0)
; #define PG8_MMA(ai, bj, At, Bt) do { __builtin_amdgcn_s_setprio(1); _Pragma("unroll") for (int m = 0; m < 4; ++m) _Pragma("unroll") for (int n = 0; n < 2; ++n) _Pragma("unroll") for (int k = 0; k < 2; ++k) \
;         acc[ai][bj][m][n] = __builtin_amdgcn_mfma_f32_16x16x32_bf16(Bt[n][k], At[m][k], acc[ai][bj][m][n], 0, 0, 0); __builtin_amdgcn_s_setprio(0); } while (0)
; #define PG8_WAIT_V(n) asm volatile("s_waitcnt vmcnt(" #n ")" ::: "memory")
; #define PG8_WAIT_L(n) asm volatile("s_waitcnt lgkmcnt(" #n ")" ::: "memory")
; #define PG8_BAR __builtin_amdgcn_s_barrier()
; #define PG8_SCHED __builtin_amdgcn_sched_barrier(0)
; template <class Epi, class Sched, bool ALIGN_EPI = false, bool SP2 = false>
; __device__ __forceinline__ void gemm_phase(PG8_LAS unsigned char* lds, const Gemm g, const Sched& S, const Epi& E, int wave_in) {
;     ...
;             PG8_WAIT_V(8); PG8_WAIT_L(0); PG8_BAR; PG8_MMA(1, 0, At, B0); PG8_MMA(1, 1, At, B1); PG8_BAR; PG8_SCHED;
;             PG8_LDB(B0, 1, 0); PG8_LDB(B1, 1, 1); PG8_SCHED; PG8_LDA(At, 1, 0); PG8_STAGE(PG8_SA(0, 1), a2 + hstep, voffA);
;             PG8_WAIT_V(8); PG8_WAIT_L(0); PG8_BAR; PG8_MMA(0, 0, At, B0); PG8_MMA(0, 1, At, B1); PG8_BAR; PG8_SCHED;
	s_setprio 3
	v_mfma_f32_16x16x32_bf16 v[60:63], v[174:177], v[190:193], v[60:63]
	v_mfma_f32_16x16x32_bf16 v[56:59], v[182:185], v[190:193], v[56:59]
	v_mfma_f32_16x16x32_bf16 v[44:47], v[174:177], v[198:201], v[44:47]
	v_mfma_f32_16x16x32_bf16 v[40:43], v[182:185], v[198:201], v[40:43]
	v_mfma_f32_16x16x32_bf16 v[28:31], v[174:177], v[206:209], v[28:31]
	v_mfma_f32_16x16x32_bf16 v[24:27], v[182:185], v[206:209], v[24:27]
	v_mfma_f32_16x16x32_bf16 v[12:15], v[174:177], v[214:217], v[12:15]
	v_mfma_f32_16x16x32_bf16 v[8:11], v[182:185], v[214:217], v[8:11]
	s_setprio 0
	s_add_i32 s50, 0, 0x18000
	s_add_i32 s51, 0, 0x1c000
	v_add_u32_e32 v166, s50, v151
	v_add_u32_e32 v182, s51, v151
	ds_read_b128 v[144:147], v166
	ds_read_b128 v[158:161], v166 offset:1024
	ds_read_b128 v[162:165], v166 offset:2048
	ds_read_b128 v[166:169], v166 offset:3072
	ds_read_b128 v[170:173], v182
	ds_read_b128 v[174:177], v182 offset:1024
	ds_read_b128 v[178:181], v182 offset:2048
	ds_read_b128 v[182:185], v182 offset:3072
	s_add_u32 s24, s24, 0x80000
	s_addc_u32 s25, s25, 0
	s_mov_b32 m0, s34
	v_lshl_add_u64 v[224:225], s[24:25], 0, v[134:135]
	ds_read_b128 v[186:189], v155 offset:32768
	ds_read_b128 v[190:193], v155 offset:33792
	ds_read_b128 v[194:197], v155 offset:34816
	ds_read_b128 v[198:201], v155 offset:35840
	ds_read_b128 v[202:205], v155 offset:36864
	ds_read_b128 v[206:209], v155 offset:37888
	ds_read_b128 v[210:213], v155 offset:38912
	ds_read_b128 v[214:217], v155 offset:39936
	global_load_lds_dwordx4 v[224:225], off
	v_lshl_add_u64 v[224:225], s[24:25], 0, v[130:131]
	s_mov_b32 m0, s35
	s_nop 0
	global_load_lds_dwordx4 v[224:225], off
	s_waitcnt vmcnt(8)
	s_waitcnt lgkmcnt(0)
	s_barrier
	s_setprio 1
	s_waitcnt lgkmcnt(0)
	v_mfma_f32_16x16x32_bf16 v[116:119], v[144:147], v[186:189], v[116:119]
	v_mfma_f32_16x16x32_bf16 v[112:115], v[162:165], v[186:189], v[112:115]
	v_mfma_f32_16x16x32_bf16 v[100:103], v[144:147], v[194:197], v[100:103]
	v_mfma_f32_16x16x32_bf16 v[96:99], v[162:165], v[194:197], v[96:99]
	v_mfma_f32_16x16x32_bf16 v[84:87], v[144:147], v[202:205], v[84:87]
	v_mfma_f32_16x16x32_bf16 v[80:83], v[162:165], v[202:205], v[80:83]
	v_mfma_f32_16x16x32_bf16 v[72:75], v[144:147], v[210:213], v[72:75]
	v_mfma_f32_16x16x32_bf16 v[64:67], v[162:165], v[210:213], v[64:67]
	v_mfma_f32_16x16x32_bf16 v[116:119], v[158:161], v[190:193], v[116:119]
	v_mfma_f32_16x16x32_bf16 v[112:115], v[166:169], v[190:193], v[112:115]
	v_mfma_f32_16x16x32_bf16 v[100:103], v[158:161], v[198:201], v[100:103]
	v_mfma_f32_16x16x32_bf16 v[96:99], v[166:169], v[198:201], v[96:99]
	v_mfma_f32_16x16x32_bf16 v[84:87], v[158:161], v[206:209], v[84:87]
	v_mfma_f32_16x16x32_bf16 v[80:83], v[166:169], v[206:209], v[80:83]
	v_mfma_f32_16x16x32_bf16 v[72:75], v[158:161], v[214:217], v[72:75]
	v_mfma_f32_16x16x32_bf16 v[64:67], v[166:169], v[214:217], v[64:67]
	s_setprio 0
	s_setprio 1
	v_mfma_f32_16x16x32_bf16 v[124:127], v[170:173], v[186:189], v[124:127]
	v_mfma_f32_16x16x32_bf16 v[120:123], v[178:181], v[186:189], v[120:123]
	v_mfma_f32_16x16x32_bf16 v[108:111], v[170:173], v[194:197], v[108:111]
	v_mfma_f32_16x16x32_bf16 v[104:107], v[178:181], v[194:197], v[104:107]
	v_mfma_f32_16x16x32_bf16 v[92:95], v[170:173], v[202:205], v[92:95]
	v_mfma_f32_16x16x32_bf16 v[88:91], v[178:181], v[202:205], v[88:91]
	v_mfma_f32_16x16x32_bf16 v[76:79], v[170:173], v[210:213], v[76:79]
	v_mfma_f32_16x16x32_bf16 v[68:71], v[178:181], v[210:213], v[68:71]
	s_barrier
; #define PG8_STAGE(bufoff, gbase, voff) do { _Pragma("unroll") for (int _i = 0; _i < 2; ++_i) \
;         __builtin_amdgcn_global_load_lds((const unsigned*)((const char*)(gbase) + (voff)[_i]), (PG8_LAS unsigned*)(lds + (bufoff) + ldsw + _i * 8192), 16, 0, 0); } while (0)
; #define PG8_LDA(dst, b, h) do { _Pragma("unroll") for (int m = 0; m < 4; ++m) _Pragma("unroll") for (int k = 0; k < 2; ++k) dst[m][k] = *(const PG8_LAS bf16x8*)(lds + PG8_SA(b, h) + aoff + m * 2048 + k * 1024); } while (0)
; #define PG8_LDB(dst, b, h) do { _Pragma("unroll") for (int n = 0; n < 2; ++n) _Pragma("unroll") for (int k = 0; k < 2; ++k) dst[n][k] = *(const PG8_LAS bf16x8*)(lds + PG8_SB(b, h) + boff + n * 2048 + k * 1024); } while (0)
; #define PG8_MMA(ai, bj, At, Bt) do { __builtin_amdgcn_s_setprio(1); _Pragma("unroll") for (int m = 0; m < 4; ++m) _Pragma("unroll") for (int n = 0; n < 2; ++n) _Pragma("unroll") for (int k = 0; k < 2; ++k) \
;         acc[ai][bj][m][n] = __builtin_amdgcn_mfma_f32_16x16x32_bf16(Bt[n][k], At[m][k], acc[ai][bj][m][n], 0, 0, 0); __builtin_amdgcn_s_setprio(0); } while (0)
; #define PG8_WAIT_V(n) asm volatile("s_waitcnt vmcnt(" #n ")" ::: "memory")
; #define PG8_WAIT_L(n) asm volatile("s_waitcnt lgkmcnt(" #n ")" ::: "memory")
; template <class Epi, class Sched, bool ALIGN_EPI = false, bool SP2 = false>
; __device__ __forceinline__ void gemm_phase(PG8_LAS unsigned char* lds, const Gemm g, const Sched& S, const Epi& E, int wave_in) {
;     ...
;             PG8_WAIT_V(8); PG8_WAIT_L(0); PG8_BAR; PG8_MMA(0, 0, At, B0); PG8_MMA(0, 1, At, B1); PG8_BAR; PG8_SCHED;
;             PG8_LDA(At, 0, 1); PG8_STAGE(PG8_SB(0, 0), b2, voffB); PG8_STAGE(PG8_SB(0, 1), b2 + hstep, voffB); PG8_STAGE(PG8_SA(0, 0), a2, voffA);
;             PG8_WAIT_V(8); PG8_WAIT_L(0); PG8_BAR; PG8_MMA(1, 0, At, B0); PG8_MMA(1, 1, At, B1); PG8_BAR; PG8_SCHED;
;             PG8_LDB(B0, 1, 0); PG8_LDB(B1, 1, 1); PG8_SCHED; PG8_LDA(At, 1, 0); PG8_STAGE(PG8_SA(0, 1), a2 + hstep, voffA);
;             PG8_WAIT_V(8); PG8_WAIT_L(0); PG8_BAR; PG8_MMA(0, 0, At, B0); PG8_MMA(0, 1, At, B1); PG8_BAR; PG8_SCHED;
;             PG8_LDA(At, 1, 1); PG8_STAGE(PG8_SB(1, 0), b3, voffB); PG8_STAGE(PG8_SB(1, 1), b3 + hstep, voffB); PG8_STAGE(PG8_SA(1, 0), a3, voffA);
;             PG8_WAIT_V(8); PG8_WAIT_L(0); PG8_BAR; PG8_MMA(1, 0, At, B0); PG8_MMA(1, 1, At, B1); PG8_BAR; PG8_SCHED;
	s_setprio 3
	v_mfma_f32_16x16x32_bf16 v[124:127], v[174:177], v[190:193], v[124:127]
	v_mfma_f32_16x16x32_bf16 v[120:123], v[182:185], v[190:193], v[120:123]
	v_mfma_f32_16x16x32_bf16 v[108:111], v[174:177], v[198:201], v[108:111]
	v_mfma_f32_16x16x32_bf16 v[104:107], v[182:185], v[198:201], v[104:107]
	v_mfma_f32_16x16x32_bf16 v[92:95], v[174:177], v[206:209], v[92:95]
	v_mfma_f32_16x16x32_bf16 v[88:91], v[182:185], v[206:209], v[88:91]
	v_mfma_f32_16x16x32_bf16 v[76:79], v[174:177], v[214:217], v[76:79]
	v_mfma_f32_16x16x32_bf16 v[68:71], v[182:185], v[214:217], v[68:71]
	s_setprio 0
	s_add_i32 s24, s50, s26
	v_lshl_add_u64 v[148:149], v[148:149], 0, s[2:3]
	s_mov_b32 m0, s24
	ds_read_b128 v[186:189], v155 offset:49152
	ds_read_b128 v[190:193], v155 offset:50176
	ds_read_b128 v[194:197], v155 offset:51200
	ds_read_b128 v[198:201], v155 offset:52224
	ds_read_b128 v[202:205], v155 offset:53248
	ds_read_b128 v[206:209], v155 offset:54272
	ds_read_b128 v[210:213], v155 offset:55296
	ds_read_b128 v[214:217], v155 offset:56320
	global_load_lds_dwordx4 v[148:149], off
	s_add_i32 m0, s24, 0x2000
	s_add_u32 s22, s22, 0x80080
	v_lshl_add_u64 v[148:149], v[218:219], 0, s[2:3]
	s_addc_u32 s23, s23, 0
	s_add_i32 s24, s51, s26
	global_load_lds_dwordx4 v[148:149], off
	v_lshl_add_u64 v[148:149], s[22:23], 0, v[132:133]
	s_mov_b32 m0, s24
	s_nop 0
	global_load_lds_dwordx4 v[148:149], off
	v_lshl_add_u64 v[148:149], s[22:23], 0, v[128:129]
	s_add_i32 m0, s24, 0x2000
	s_nop 0
	global_load_lds_dwordx4 v[148:149], off
	v_lshl_add_u64 v[148:149], v[220:221], 0, s[2:3]
	s_mov_b32 m0, s37
	s_nop 0
	global_load_lds_dwordx4 v[148:149], off
	v_lshl_add_u64 v[148:149], v[222:223], 0, s[2:3]
	s_mov_b32 m0, s38
	s_nop 0
	global_load_lds_dwordx4 v[148:149], off
	s_waitcnt vmcnt(8)
	s_waitcnt lgkmcnt(0)
	s_barrier
	s_setprio 1
	s_waitcnt lgkmcnt(0)
	v_mfma_f32_16x16x32_bf16 v[52:55], v[144:147], v[186:189], v[52:55]
	v_mfma_f32_16x16x32_bf16 v[48:51], v[162:165], v[186:189], v[48:51]
	v_mfma_f32_16x16x32_bf16 v[36:39], v[144:147], v[194:197], v[36:39]
	v_mfma_f32_16x16x32_bf16 v[32:35], v[162:165], v[194:197], v[32:35]
	v_mfma_f32_16x16x32_bf16 v[20:23], v[144:147], v[202:205], v[20:23]
	v_mfma_f32_16x16x32_bf16 v[16:19], v[162:165], v[202:205], v[16:19]
	v_mfma_f32_16x16x32_bf16 v[4:7], v[144:147], v[210:213], v[4:7]
	v_mfma_f32_16x16x32_bf16 v[0:3], v[162:165], v[210:213], v[0:3]
	v_mfma_f32_16x16x32_bf16 v[52:55], v[158:161], v[190:193], v[52:55]
	v_mfma_f32_16x16x32_bf16 v[48:51], v[166:169], v[190:193], v[48:51]
	v_mfma_f32_16x16x32_bf16 v[36:39], v[158:161], v[198:201], v[36:39]
	v_mfma_f32_16x16x32_bf16 v[32:35], v[166:169], v[198:201], v[32:35]
	v_mfma_f32_16x16x32_bf16 v[20:23], v[158:161], v[206:209], v[20:23]
	v_mfma_f32_16x16x32_bf16 v[16:19], v[166:169], v[206:209], v[16:19]
	v_mfma_f32_16x16x32_bf16 v[4:7], v[158:161], v[214:217], v[4:7]
	v_mfma_f32_16x16x32_bf16 v[0:3], v[166:169], v[214:217], v[0:3]
	s_setprio 0
	s_setprio 1
	v_mfma_f32_16x16x32_bf16 v[60:63], v[170:173], v[186:189], v[60:63]
	v_mfma_f32_16x16x32_bf16 v[56:59], v[178:181], v[186:189], v[56:59]
	v_mfma_f32_16x16x32_bf16 v[44:47], v[170:173], v[194:197], v[44:47]
	v_mfma_f32_16x16x32_bf16 v[40:43], v[178:181], v[194:197], v[40:43]
	v_mfma_f32_16x16x32_bf16 v[28:31], v[170:173], v[202:205], v[28:31]
	v_mfma_f32_16x16x32_bf16 v[24:27], v[178:181], v[202:205], v[24:27]
	v_mfma_f32_16x16x32_bf16 v[12:15], v[170:173], v[210:213], v[12:15]
	v_mfma_f32_16x16x32_bf16 v[8:11], v[178:181], v[210:213], v[8:11]
	s_barrier
	s_setprio 3
	v_mfma_f32_16x16x32_bf16 v[60:63], v[174:177], v[190:193], v[60:63]
	v_mfma_f32_16x16x32_bf16 v[56:59], v[182:185], v[190:193], v[56:59]
	v_mfma_f32_16x16x32_bf16 v[44:47], v[174:177], v[198:201], v[44:47]
	v_mfma_f32_16x16x32_bf16 v[40:43], v[182:185], v[198:201], v[40:43]
	v_mfma_f32_16x16x32_bf16 v[28:31], v[174:177], v[206:209], v[28:31]
	v_mfma_f32_16x16x32_bf16 v[24:27], v[182:185], v[206:209], v[24:27]
	v_mfma_f32_16x16x32_bf16 v[12:15], v[174:177], v[214:217], v[12:15]
	v_mfma_f32_16x16x32_bf16 v[8:11], v[182:185], v[214:217], v[8:11]
	s_setprio 0
	s_add_i32 s49, s49, 2
	s_add_u32 s20, s20, 0x100
	s_addc_u32 s21, s21, 0
	s_add_u32 s47, s47, 0x100
	s_addc_u32 s48, s48, 0
	s_cmp_gt_u32 s49, 29
	s_cbranch_scc0 .LBB0_929
	s_and_b64 vcc, exec, s[8:9]
	s_cbranch_vccz .LBB0_932
	s_barrier

; #define PG8_STAGE(bufoff, gbase, voff) do { _Pragma("unroll") for (int _i = 0; _i < 2; ++_i) \
;         __builtin_amdgcn_global_load_lds((const unsigned*)((const char*)(gbase) + (voff)[_i]), (PG8_LAS unsigned*)(lds + (bufoff) + ldsw + _i * 8192), 16, 0, 0); } while (0)
; #define PG8_LDA(dst, b, h) do { _Pragma("unroll") for (int m = 0; m < 4; ++m) _Pragma("unroll") for (int k = 0; k < 2; ++k) dst[m][k] = *(const PG8_LAS bf16x8*)(lds + PG8_SA(b, h) + aoff + m * 2048 + k * 1024); } while (0)
; #define PG8_LDB(dst, b, h) do { _Pragma("unroll") for (int n = 0; n < 2; ++n) _Pragma("unroll") for (int k = 0; k < 2; ++k) dst[n][k] = *(const PG8_LAS bf16x8*)(lds + PG8_SB(b, h) + boff + n * 2048 + k * 1024); } while (0)
; #define PG8_BAR __builtin_amdgcn_s_barrier()
; template <class Epi, class Sched, bool ALIGN_EPI = false, bool SP2 = false>
; __device__ __forceinline__ void gemm_phase(PG8_LAS unsigned char* lds, const Gemm g, const Sched& S, const Epi& E, int wave_in) {
;     ...
;         const bool has_next = S.next(ui + 1, nxt);
;         const char* nA = has_next ? (const char*)g.A + (size_t)nxt.pm * tstep : cA; const char* nB = has_next ? (const char*)g.Bt + (size_t)nxt.pn * tstep : cB;
;         for (int t = 0; t < nt; t += 2) {
;             const bool last = (t == nt - 2);
;             const char* a1 = cA + (size_t)(t + 1) * kstep;
;             const char* a2 = last ? nA : cA + (size_t)(t + 2) * kstep; const char* b2 = last ? nB : cB + (size_t)(t + 2) * kstep;
;             const char* a3 = a2 + kstep; const char* b3 = b2 + kstep;
;             if (last && has_next) S.a_ready(nxt);
;             if constexpr (SP2) {
;             PG8_LDB(B0, 0, 0); PG8_LDB(B1, 0, 1); PG8_SCHED; PG8_LDA(At, 0, 0); PG8_STAGE(PG8_SA(1, 1), a1 + hstep, voffA);
;             PG8_WAIT_V(8); PG8_WAIT_L(0); PG8_BAR; PG8_MMA(0, 0, At, B0); PG8_MMA(0, 1, At, B1); PG8_BAR; PG8_SCHED;
;             PG8_LDA(At, 0, 1); PG8_STAGE(PG8_SB(0, 0), b2, voffB); PG8_STAGE(PG8_SB(0, 1), b2 + hstep, voffB); PG8_STAGE(PG8_SA(0, 0), a2, voffA);
;             PG8_WAIT_V(8); PG8_WAIT_L(0); PG8_BAR; PG8_MMA(1, 0, At, B0); PG8_MMA(1, 1, At, B1); PG8_BAR; PG8_SCHED;
;             PG8_LDB(B0, 1, 0); PG8_LDB(B1, 1, 1); PG8_SCHED; PG8_LDA(At, 1, 0); PG8_STAGE(PG8_SA(0, 1), a2 + hstep, voffA);
;             PG8_WAIT_V(8); PG8_WAIT_L(0); PG8_BAR; PG8_MMA(0, 0, At, B0); PG8_MMA(0, 1, At, B1); PG8_BAR; PG8_SCHED;
.LBB0_1009:
	ds_read_b128 v[140:143], v147
	ds_read_b128 v[150:153], v147 offset:1024
	ds_read_b128 v[154:157], v147 offset:2048
	ds_read_b128 v[158:161], v147 offset:3072
	ds_read_b128 v[162:165], v148
	ds_read_b128 v[166:169], v148 offset:1024
	ds_read_b128 v[170:173], v148 offset:2048
	ds_read_b128 v[174:177], v148 offset:3072
	s_add_u32 s18, s16, 0x100
	s_addc_u32 s19, s17, 0
	s_cmpk_eq_i32 s45, 0x54
	s_cselect_b32 s23, s5, s19
	s_cselect_b32 s22, s4, s18
	s_cselect_b32 s21, s15, s44
	s_cselect_b32 s20, s14, s43
	v_lshl_add_u64 v[210:211], s[16:17], 0, v[132:133]
	s_add_i32 m0, s28, 0xc000
	ds_read_b128 v[178:181], v149
	ds_read_b128 v[182:185], v149 offset:1024
	ds_read_b128 v[186:189], v149 offset:2048
	ds_read_b128 v[190:193], v149 offset:3072
	ds_read_b128 v[194:197], v149 offset:4096
	ds_read_b128 v[198:201], v149 offset:5120
	ds_read_b128 v[202:205], v149 offset:6144
	ds_read_b128 v[206:209], v149 offset:7168
	global_load_lds_dwordx4 v[210:211], off
	v_lshl_add_u64 v[210:211], s[16:17], 0, v[134:135]
	s_add_i32 m0, s28, 0xe000
	s_nop 0
	global_load_lds_dwordx4 v[210:211], off
	s_waitcnt vmcnt(8)
	s_waitcnt lgkmcnt(0)
	s_barrier
	s_setprio 1
	s_waitcnt lgkmcnt(0)
	v_mfma_f32_16x16x32_bf16 v[124:127], v[140:143], v[178:181], v[124:127]
	v_mfma_f32_16x16x32_bf16 v[120:123], v[154:157], v[178:181], v[120:123]
	v_mfma_f32_16x16x32_bf16 v[112:115], v[140:143], v[186:189], v[112:115]
	v_mfma_f32_16x16x32_bf16 v[104:107], v[154:157], v[186:189], v[104:107]
	v_mfma_f32_16x16x32_bf16 v[96:99], v[140:143], v[194:197], v[96:99]
	v_mfma_f32_16x16x32_bf16 v[88:91], v[154:157], v[194:197], v[88:91]
	v_mfma_f32_16x16x32_bf16 v[80:83], v[140:143], v[202:205], v[80:83]
	v_mfma_f32_16x16x32_bf16 v[72:75], v[154:157], v[202:205], v[72:75]
	v_mfma_f32_16x16x32_bf16 v[124:127], v[150:153], v[182:185], v[124:127]
	v_mfma_f32_16x16x32_bf16 v[120:123], v[158:161], v[182:185], v[120:123]
	v_mfma_f32_16x16x32_bf16 v[112:115], v[150:153], v[190:193], v[112:115]
	v_mfma_f32_16x16x32_bf16 v[104:107], v[158:161], v[190:193], v[104:107]
	v_mfma_f32_16x16x32_bf16 v[96:99], v[150:153], v[198:201], v[96:99]
	v_mfma_f32_16x16x32_bf16 v[88:91], v[158:161], v[198:201], v[88:91]
	v_mfma_f32_16x16x32_bf16 v[80:83], v[150:153], v[206:209], v[80:83]
	v_mfma_f32_16x16x32_bf16 v[72:75], v[158:161], v[206:209], v[72:75]
	s_setprio 0
	s_setprio 1
	v_mfma_f32_16x16x32_bf16 v[116:119], v[162:165], v[178:181], v[116:119]
	v_mfma_f32_16x16x32_bf16 v[108:111], v[170:173], v[178:181], v[108:111]
	v_mfma_f32_16x16x32_bf16 v[100:103], v[162:165], v[186:189], v[100:103]
	v_mfma_f32_16x16x32_bf16 v[92:95], v[170:173], v[186:189], v[92:95]
	v_mfma_f32_16x16x32_bf16 v[84:87], v[162:165], v[194:197], v[84:87]
	v_mfma_f32_16x16x32_bf16 v[76:79], v[170:173], v[194:197], v[76:79]
	v_mfma_f32_16x16x32_bf16 v[68:71], v[162:165], v[202:205], v[68:71]
	v_mfma_f32_16x16x32_bf16 v[64:67], v[170:173], v[202:205], v[64:67]
	s_barrier
	s_setprio 3
	v_mfma_f32_16x16x32_bf16 v[116:119], v[166:169], v[182:185], v[116:119]
	v_mfma_f32_16x16x32_bf16 v[108:111], v[174:177], v[182:185], v[108:111]
	v_mfma_f32_16x16x32_bf16 v[100:103], v[166:169], v[190:193], v[100:103]
	v_mfma_f32_16x16x32_bf16 v[92:95], v[174:177], v[190:193], v[92:95]
	v_mfma_f32_16x16x32_bf16 v[84:87], v[166:169], v[198:201], v[84:87]
	v_mfma_f32_16x16x32_bf16 v[76:79], v[174:177], v[198:201], v[76:79]
	v_mfma_f32_16x16x32_bf16 v[68:71], v[166:169], v[206:209], v[68:71]
	v_mfma_f32_16x16x32_bf16 v[64:67], v[174:177], v[206:209], v[64:67]
	s_setprio 0
	s_add_i32 s16, s37, s25
	v_lshl_add_u64 v[210:211], s[20:21], 0, v[128:129]
	s_mov_b32 m0, s16
	ds_read_b128 v[178:181], v149 offset:16384
	ds_read_b128 v[182:185], v149 offset:17408
	ds_read_b128 v[186:189], v149 offset:18432
	ds_read_b128 v[190:193], v149 offset:19456
	ds_read_b128 v[194:197], v149 offset:20480
	ds_read_b128 v[198:201], v149 offset:21504
	ds_read_b128 v[202:205], v149 offset:22528
	ds_read_b128 v[206:209], v149 offset:23552
	global_load_lds_dwordx4 v[210:211], off
	s_add_i32 m0, s16, 0x2000
	s_add_u32 s16, s20, 0x160000
	v_lshl_add_u64 v[212:213], s[20:21], 0, v[130:131]
	s_addc_u32 s17, s21, 0
	s_add_i32 s46, s38, s25
	global_load_lds_dwordx4 v[212:213], off
	v_lshl_add_u64 v[214:215], s[16:17], 0, v[128:129]
	s_mov_b32 m0, s46
	v_lshl_add_u64 v[216:217], s[22:23], 0, v[130:131]
	global_load_lds_dwordx4 v[214:215], off
	v_lshl_add_u64 v[214:215], s[16:17], 0, v[130:131]
	s_add_i32 m0, s46, 0x2000
	s_nop 0
	global_load_lds_dwordx4 v[214:215], off
	v_lshl_add_u64 v[214:215], s[22:23], 0, v[128:129]
	s_mov_b32 m0, s28
	s_nop 0
	global_load_lds_dwordx4 v[214:215], off
	s_mov_b32 m0, s29
	s_nop 0
	global_load_lds_dwordx4 v[216:217], off
	s_waitcnt vmcnt(8)
	s_waitcnt lgkmcnt(0)
	s_barrier
	s_setprio 1
	s_waitcnt lgkmcnt(0)
	v_mfma_f32_16x16x32_bf16 v[60:63], v[140:143], v[178:181], v[60:63]
	v_mfma_f32_16x16x32_bf16 v[56:59], v[154:157], v[178:181], v[56:59]
	v_mfma_f32_16x16x32_bf16 v[48:51], v[140:143], v[186:189], v[48:51]
	v_mfma_f32_16x16x32_bf16 v[40:43], v[154:157], v[186:189], v[40:43]
	v_mfma_f32_16x16x32_bf16 v[32:35], v[140:143], v[194:197], v[32:35]
	v_mfma_f32_16x16x32_bf16 v[24:27], v[154:157], v[194:197], v[24:27]
	v_mfma_f32_16x16x32_bf16 v[16:19], v[140:143], v[202:205], v[16:19]
	v_mfma_f32_16x16x32_bf16 v[8:11], v[154:157], v[202:205], v[8:11]
	v_mfma_f32_16x16x32_bf16 v[60:63], v[150:153], v[182:185], v[60:63]
	v_mfma_f32_16x16x32_bf16 v[56:59], v[158:161], v[182:185], v[56:59]
	v_mfma_f32_16x16x32_bf16 v[48:51], v[150:153], v[190:193], v[48:51]
	v_mfma_f32_16x16x32_bf16 v[40:43], v[158:161], v[190:193], v[40:43]
	v_mfma_f32_16x16x32_bf16 v[32:35], v[150:153], v[198:201], v[32:35]
	v_mfma_f32_16x16x32_bf16 v[24:27], v[158:161], v[198:201], v[24:27]
	v_mfma_f32_16x16x32_bf16 v[16:19], v[150:153], v[206:209], v[16:19]
	v_mfma_f32_16x16x32_bf16 v[8:11], v[158:161], v[206:209], v[8:11]
	s_setprio 0
	s_setprio 1
	v_mfma_f32_16x16x32_bf16 v[52:55], v[162:165], v[178:181], v[52:55]
	v_mfma_f32_16x16x32_bf16 v[44:47], v[170:173], v[178:181], v[44:47]
	v_mfma_f32_16x16x32_bf16 v[36:39], v[162:165], v[186:189], v[36:39]
	v_mfma_f32_16x16x32_bf16 v[28:31], v[170:173], v[186:189], v[28:31]
	v_mfma_f32_16x16x32_bf16 v[20:23], v[162:165], v[194:197], v[20:23]
	v_mfma_f32_16x16x32_bf16 v[12:15], v[170:173], v[194:197], v[12:15]
	v_mfma_f32_16x16x32_bf16 v[4:7], v[162:165], v[202:205], v[4:7]
	v_mfma_f32_16x16x32_bf16 v[0:3], v[170:173], v[202:205], v[0:3]
	s_barrier
; #define PG8_STAGE(bufoff, gbase, voff) do { _Pragma("unroll") for (int _i = 0; _i < 2; ++_i) \
;         __builtin_amdgcn_global_load_lds((const unsigned*)((const char*)(gbase) + (voff)[_i]), (PG8_LAS unsigned*)(lds + (bufoff) + ldsw + _i * 8192), 16, 0, 0); } while (0)
; #define PG8_LDA(dst, b, h) do { _Pragma("unroll") for (int m = 0; m < 4; ++m) _Pragma("unroll") for (int k = 0; k < 2; ++k) dst[m][k] = *(const PG8_LAS bf16x8*)(lds + PG8_SA(b, h) + aoff + m * 2048 + k * 1024); } while (0)
; #define PG8_LDB(dst, b, h) do { _Pragma("unroll") for (int n = 0; n < 2; ++n) _Pragma("unroll") for (int k = 0; k < 2; ++k) dst[n][k] = *(const PG8_LAS bf16x8*)(lds + PG8_SB(b, h) + boff + n * 2048 + k * 1024); } while (0)
; #define PG8_MMA(ai, bj, At, Bt) do { __builtin_amdgcn_s_setprio(1); _Pragma("unroll") for (int m = 0; m < 4; ++m) _Pragma("unroll") for (int n = 0; n < 2; ++n) _Pragma("unroll") for (int k = 0; k < 2; ++k) \
;         acc[ai][bj][m][n] = __builtin_amdgcn_mfma_f32_16x16x32_bf16(Bt[n][k], At[m][k], acc[ai][bj][m][n], 0, 0, 0); __builtin_amdgcn_s_setprio(0); } while (0)
; #define PG8_WAIT_V(n) asm volatile("s_waitcnt vmcnt(" #n ")" ::: "memory")
; #define PG8_WAIT_L(n) asm volatile("s_waitcnt lgkmcnt(" #n ")" ::: "memory")
; #define PG8_BAR __builtin_amdgcn_s_barrier()
; #define PG8_SCHED __builtin_amdgcn_sched_barrier(0)
; template <class Epi, class Sched, bool ALIGN_EPI = false, bool SP2 = false>
; __device__ __forceinline__ void gemm_phase(PG8_LAS unsigned char* lds, const Gemm g, const Sched& S, const Epi& E, int wave_in) {
;     ...
;             PG8_WAIT_V(8); PG8_WAIT_L(0); PG8_BAR; PG8_MMA(1, 0, At, B0); PG8_MMA(1, 1, At, B1); PG8_BAR; PG8_SCHED;
;             PG8_LDB(B0, 1, 0); PG8_LDB(B1, 1, 1); PG8_SCHED; PG8_LDA(At, 1, 0); PG8_STAGE(PG8_SA(0, 1), a2 + hstep, voffA);
;             PG8_WAIT_V(8); PG8_WAIT_L(0); PG8_BAR; PG8_MMA(0, 0, At, B0); PG8_MMA(0, 1, At, B1); PG8_BAR; PG8_SCHED;
;             PG8_LDA(At, 1, 1); PG8_STAGE(PG8_SB(1, 0), b3, voffB); PG8_STAGE(PG8_SB(1, 1), b3 + hstep, voffB); PG8_STAGE(PG8_SA(1, 0), a3, voffA);
;             PG8_WAIT_V(8); PG8_WAIT_L(0); PG8_BAR; PG8_MMA(1, 0, At, B0); PG8_MMA(1, 1, At, B1); PG8_BAR; PG8_SCHED;
	s_setprio 3
	v_mfma_f32_16x16x32_bf16 v[52:55], v[166:169], v[182:185], v[52:55]
	v_mfma_f32_16x16x32_bf16 v[44:47], v[174:177], v[182:185], v[44:47]
	v_mfma_f32_16x16x32_bf16 v[36:39], v[166:169], v[190:193], v[36:39]
	v_mfma_f32_16x16x32_bf16 v[28:31], v[174:177], v[190:193], v[28:31]
	v_mfma_f32_16x16x32_bf16 v[20:23], v[166:169], v[198:201], v[20:23]
	v_mfma_f32_16x16x32_bf16 v[12:15], v[174:177], v[198:201], v[12:15]
	v_mfma_f32_16x16x32_bf16 v[4:7], v[166:169], v[206:209], v[4:7]
	v_mfma_f32_16x16x32_bf16 v[0:3], v[174:177], v[206:209], v[0:3]
	s_setprio 0
	s_add_i32 s46, 0, 0x18000
	s_add_i32 s47, 0, 0x1c000
	v_add_u32_e32 v158, s46, v145
	v_add_u32_e32 v174, s47, v145
	ds_read_b128 v[140:143], v158
	ds_read_b128 v[150:153], v158 offset:1024
	ds_read_b128 v[154:157], v158 offset:2048
	ds_read_b128 v[158:161], v158 offset:3072
	ds_read_b128 v[162:165], v174
	ds_read_b128 v[166:169], v174 offset:1024
	ds_read_b128 v[170:173], v174 offset:2048
	ds_read_b128 v[174:177], v174 offset:3072
	s_add_u32 s16, s22, 0x160000
	s_addc_u32 s17, s23, 0
	s_mov_b32 m0, s30
	v_lshl_add_u64 v[218:219], s[16:17], 0, v[128:129]
	ds_read_b128 v[178:181], v149 offset:32768
	ds_read_b128 v[182:185], v149 offset:33792
	ds_read_b128 v[186:189], v149 offset:34816
	ds_read_b128 v[190:193], v149 offset:35840
	ds_read_b128 v[194:197], v149 offset:36864
	ds_read_b128 v[198:201], v149 offset:37888
	ds_read_b128 v[202:205], v149 offset:38912
	ds_read_b128 v[206:209], v149 offset:39936
	global_load_lds_dwordx4 v[218:219], off
	v_lshl_add_u64 v[218:219], s[16:17], 0, v[130:131]
	s_mov_b32 m0, s31
	s_nop 0
	global_load_lds_dwordx4 v[218:219], off
	s_waitcnt vmcnt(8)
	s_waitcnt lgkmcnt(0)
	s_barrier
	s_setprio 1
	s_waitcnt lgkmcnt(0)
	v_mfma_f32_16x16x32_bf16 v[124:127], v[140:143], v[178:181], v[124:127]
	v_mfma_f32_16x16x32_bf16 v[120:123], v[154:157], v[178:181], v[120:123]
	v_mfma_f32_16x16x32_bf16 v[112:115], v[140:143], v[186:189], v[112:115]
	v_mfma_f32_16x16x32_bf16 v[104:107], v[154:157], v[186:189], v[104:107]
	v_mfma_f32_16x16x32_bf16 v[96:99], v[140:143], v[194:197], v[96:99]
	v_mfma_f32_16x16x32_bf16 v[88:91], v[154:157], v[194:197], v[88:91]
	v_mfma_f32_16x16x32_bf16 v[80:83], v[140:143], v[202:205], v[80:83]
	v_mfma_f32_16x16x32_bf16 v[72:75], v[154:157], v[202:205], v[72:75]
	v_mfma_f32_16x16x32_bf16 v[124:127], v[150:153], v[182:185], v[124:127]
	v_mfma_f32_16x16x32_bf16 v[120:123], v[158:161], v[182:185], v[120:123]
	v_mfma_f32_16x16x32_bf16 v[112:115], v[150:153], v[190:193], v[112:115]
	v_mfma_f32_16x16x32_bf16 v[104:107], v[158:161], v[190:193], v[104:107]
	v_mfma_f32_16x16x32_bf16 v[96:99], v[150:153], v[198:201], v[96:99]
	v_mfma_f32_16x16x32_bf16 v[88:91], v[158:161], v[198:201], v[88:91]
	v_mfma_f32_16x16x32_bf16 v[80:83], v[150:153], v[206:209], v[80:83]
	v_mfma_f32_16x16x32_bf16 v[72:75], v[158:161], v[206:209], v[72:75]
	s_setprio 0
	s_setprio 1
	v_mfma_f32_16x16x32_bf16 v[116:119], v[162:165], v[178:181], v[116:119]
	v_mfma_f32_16x16x32_bf16 v[108:111], v[170:173], v[178:181], v[108:111]
	v_mfma_f32_16x16x32_bf16 v[100:103], v[162:165], v[186:189], v[100:103]
	v_mfma_f32_16x16x32_bf16 v[92:95], v[170:173], v[186:189], v[92:95]
	v_mfma_f32_16x16x32_bf16 v[84:87], v[162:165], v[194:197], v[84:87]
	v_mfma_f32_16x16x32_bf16 v[76:79], v[170:173], v[194:197], v[76:79]
	v_mfma_f32_16x16x32_bf16 v[68:71], v[162:165], v[202:205], v[68:71]
	v_mfma_f32_16x16x32_bf16 v[64:67], v[170:173], v[202:205], v[64:67]
	s_barrier
	s_setprio 3
	v_mfma_f32_16x16x32_bf16 v[116:119], v[166:169], v[182:185], v[116:119]
	v_mfma_f32_16x16x32_bf16 v[108:111], v[174:177], v[182:185], v[108:111]
	v_mfma_f32_16x16x32_bf16 v[100:103], v[166:169], v[190:193], v[100:103]
	v_mfma_f32_16x16x32_bf16 v[92:95], v[174:177], v[190:193], v[92:95]
	v_mfma_f32_16x16x32_bf16 v[84:87], v[166:169], v[198:201], v[84:87]
	v_mfma_f32_16x16x32_bf16 v[76:79], v[174:177], v[198:201], v[76:79]
	v_mfma_f32_16x16x32_bf16 v[68:71], v[166:169], v[206:209], v[68:71]
	v_mfma_f32_16x16x32_bf16 v[64:67], v[174:177], v[206:209], v[64:67]
	s_setprio 0
	s_add_i32 s16, s46, s25
	v_lshl_add_u64 v[210:211], v[210:211], 0, s[6:7]
	s_mov_b32 m0, s16
	ds_read_b128 v[178:181], v149 offset:49152
	ds_read_b128 v[182:185], v149 offset:50176
	ds_read_b128 v[186:189], v149 offset:51200
	ds_read_b128 v[190:193], v149 offset:52224
	ds_read_b128 v[194:197], v149 offset:53248
	ds_read_b128 v[198:201], v149 offset:54272
	ds_read_b128 v[202:205], v149 offset:55296
	ds_read_b128 v[206:209], v149 offset:56320
	global_load_lds_dwordx4 v[210:211], off
	s_add_i32 m0, s16, 0x2000
	s_add_u32 s16, s20, 0x160080
	v_lshl_add_u64 v[210:211], v[212:213], 0, s[6:7]
	s_addc_u32 s17, s21, 0
	s_add_i32 s20, s47, s25
	global_load_lds_dwordx4 v[210:211], off
	v_lshl_add_u64 v[210:211], s[16:17], 0, v[128:129]
	s_mov_b32 m0, s20
	s_nop 0
	global_load_lds_dwordx4 v[210:211], off
	v_lshl_add_u64 v[210:211], s[16:17], 0, v[130:131]
	s_add_i32 m0, s20, 0x2000
	s_nop 0
	global_load_lds_dwordx4 v[210:211], off
	v_lshl_add_u64 v[210:211], v[214:215], 0, s[6:7]
	s_mov_b32 m0, s34
	s_nop 0
	global_load_lds_dwordx4 v[210:211], off
	v_lshl_add_u64 v[210:211], v[216:217], 0, s[6:7]
	s_mov_b32 m0, s35
	s_nop 0
	global_load_lds_dwordx4 v[210:211], off
	s_waitcnt vmcnt(8)
	s_waitcnt lgkmcnt(0)
	s_barrier
; #define PG8_WAIT_V(n) asm volatile("s_waitcnt vmcnt(" #n ")" ::: "memory")
;     __device__ __forceinline__ void operator()(const f32x4 (&acc)[2][2][4][2], const Unit& u, int wr, int wc, int fr, int fq) const {
;     ...
;         const int col0 = u.pn * BM + wc * 32 + 4 * fq;
; #pragma unroll
;         for (int ai = 0; ai < 2; ++ai)
; #pragma unroll
;             for (int m = 0; m < 4; ++m) { const size_t off = (size_t)(u.pm * BM + ai * HALF + wr * 64 + m * 16 + fr) * ldc + col0;
; #pragma unroll
;                 for (int bj = 0; bj < 2; ++bj)
; #pragma unroll
;                     for (int n = 0; n < 2; ++n) { const u32x2 t = *(const u32x2*)(base + off + bj * HALF + n * 16);
; template <class Epi, class Sched, bool ALIGN_EPI = false, bool SP2 = false>
; __device__ __forceinline__ void gemm_phase(PG8_LAS unsigned char* lds, const Gemm g, const Sched& S, const Epi& E, int wave_in) {
;     ...
;             PG8_WAIT_V(8); PG8_WAIT_L(0); PG8_BAR; PG8_MMA(1, 0, At, B0); PG8_MMA(1, 1, At, B1); PG8_BAR; PG8_SCHED;
;             } else {
;             PG8_LDB(B0, 0, 0); PG8_SCHED; PG8_LDA(At, 0, 0); PG8_STAGE(PG8_SA(1, 1), a1 + hstep, voffA);
;             PG8_WAIT_L(8); PG8_BAR; PG8_WAIT_L(0); PG8_MMA(0, 0, At, B0); PG8_BAR; PG8_SCHED;
;             PG8_LDB(B1, 0, 1); PG8_STAGE(PG8_SB(0, 0), b2, voffB);
;             PG8_BAR; PG8_WAIT_L(0); PG8_MMA(0, 1, At, B1); PG8_BAR;
;             PG8_LDA(At, 0, 1); PG8_STAGE(PG8_SA(0, 0), a2, voffA);
;             PG8_BAR; PG8_WAIT_L(0); PG8_MMA(1, 0, At, B0); PG8_BAR; PG8_SCHED;
;             PG8_STAGE(PG8_SB(0, 1), b2 + hstep, voffB);
;             PG8_WAIT_V(6); PG8_BAR; PG8_MMA(1, 1, At, B1); PG8_BAR;
;             PG8_LDB(B0, 1, 0); PG8_SCHED; PG8_LDA(At, 1, 0); PG8_STAGE(PG8_SA(0, 1), a2 + hstep, voffA);
;             PG8_WAIT_L(8); PG8_BAR; PG8_WAIT_L(0); PG8_MMA(0, 0, At, B0); PG8_BAR; PG8_SCHED;
;             PG8_LDB(B1, 1, 1); PG8_STAGE(PG8_SB(1, 0), b3, voffB);
;             PG8_BAR; PG8_WAIT_L(0); PG8_MMA(0, 1, At, B1); PG8_BAR;
;             PG8_LDA(At, 1, 1); PG8_STAGE(PG8_SA(1, 0), a3, voffA);
;             PG8_BAR; PG8_WAIT_L(0); PG8_MMA(1, 0, At, B0); PG8_BAR; PG8_SCHED;
;             PG8_STAGE(PG8_SB(1, 1), b3 + hstep, voffB);
;             PG8_WAIT_V(6); PG8_BAR; PG8_MMA(1, 1, At, B1); PG8_BAR;
;             }
;         }
;         if constexpr (ALIGN_EPI) { if (wr == 0) PG8_BAR; }
	s_setprio 1
	s_waitcnt lgkmcnt(0)
	v_mfma_f32_16x16x32_bf16 v[60:63], v[140:143], v[178:181], v[60:63]
	v_mfma_f32_16x16x32_bf16 v[56:59], v[154:157], v[178:181], v[56:59]
	v_mfma_f32_16x16x32_bf16 v[48:51], v[140:143], v[186:189], v[48:51]
	v_mfma_f32_16x16x32_bf16 v[40:43], v[154:157], v[186:189], v[40:43]
	v_mfma_f32_16x16x32_bf16 v[32:35], v[140:143], v[194:197], v[32:35]
	v_mfma_f32_16x16x32_bf16 v[24:27], v[154:157], v[194:197], v[24:27]
	v_mfma_f32_16x16x32_bf16 v[16:19], v[140:143], v[202:205], v[16:19]
	v_mfma_f32_16x16x32_bf16 v[8:11], v[154:157], v[202:205], v[8:11]
	v_mfma_f32_16x16x32_bf16 v[60:63], v[150:153], v[182:185], v[60:63]
	v_mfma_f32_16x16x32_bf16 v[56:59], v[158:161], v[182:185], v[56:59]
	v_mfma_f32_16x16x32_bf16 v[48:51], v[150:153], v[190:193], v[48:51]
	v_mfma_f32_16x16x32_bf16 v[40:43], v[158:161], v[190:193], v[40:43]
	v_mfma_f32_16x16x32_bf16 v[32:35], v[150:153], v[198:201], v[32:35]
	v_mfma_f32_16x16x32_bf16 v[24:27], v[158:161], v[198:201], v[24:27]
	v_mfma_f32_16x16x32_bf16 v[16:19], v[150:153], v[206:209], v[16:19]
	v_mfma_f32_16x16x32_bf16 v[8:11], v[158:161], v[206:209], v[8:11]
	s_setprio 0
	s_setprio 1
	v_mfma_f32_16x16x32_bf16 v[52:55], v[162:165], v[178:181], v[52:55]
	v_mfma_f32_16x16x32_bf16 v[44:47], v[170:173], v[178:181], v[44:47]
	v_mfma_f32_16x16x32_bf16 v[36:39], v[162:165], v[186:189], v[36:39]
	v_mfma_f32_16x16x32_bf16 v[28:31], v[170:173], v[186:189], v[28:31]
	v_mfma_f32_16x16x32_bf16 v[20:23], v[162:165], v[194:197], v[20:23]
	v_mfma_f32_16x16x32_bf16 v[12:15], v[170:173], v[194:197], v[12:15]
	v_mfma_f32_16x16x32_bf16 v[4:7], v[162:165], v[202:205], v[4:7]
	v_mfma_f32_16x16x32_bf16 v[0:3], v[170:173], v[202:205], v[0:3]
	s_barrier
	s_setprio 3
	v_mfma_f32_16x16x32_bf16 v[52:55], v[166:169], v[182:185], v[52:55]
	v_mfma_f32_16x16x32_bf16 v[44:47], v[174:177], v[182:185], v[44:47]
	v_mfma_f32_16x16x32_bf16 v[36:39], v[166:169], v[190:193], v[36:39]
	v_mfma_f32_16x16x32_bf16 v[28:31], v[174:177], v[190:193], v[28:31]
	v_mfma_f32_16x16x32_bf16 v[20:23], v[166:169], v[198:201], v[20:23]
	v_mfma_f32_16x16x32_bf16 v[12:15], v[174:177], v[198:201], v[12:15]
	v_mfma_f32_16x16x32_bf16 v[4:7], v[166:169], v[206:209], v[4:7]
	v_mfma_f32_16x16x32_bf16 v[0:3], v[174:177], v[206:209], v[0:3]
	s_setprio 0
	s_add_i32 s45, s45, 2
	s_add_u32 s43, s43, 0x100
	s_addc_u32 s44, s44, 0
	s_cmpk_gt_u32 s45, 0x55
	s_mov_b64 s[16:17], s[18:19]
	s_cbranch_scc0 .LBB0_1009
	v_lshl_add_u32 v142, s41, 8, v144
	v_lshl_or_b32 v140, s42, 8, v146
	v_lshlrev_b32_e32 v143, 12, v142
	v_lshl_add_u32 v143, v140, 1, v143
	v_mov_b32_e32 v140, v143
	global_load_dwordx2 v[152:153], v140, s[10:11]
	global_load_dwordx2 v[154:155], v140, s[10:11] offset:32
	global_load_dwordx2 v[156:157], v140, s[10:11] offset:256
	global_load_dwordx2 v[158:159], v140, s[10:11] offset:288
	v_add_u32_e32 v140, 0x10000, v143
	global_load_dwordx2 v[160:161], v140, s[10:11]
	global_load_dwordx2 v[162:163], v140, s[10:11] offset:32
	global_load_dwordx2 v[164:165], v140, s[10:11] offset:256
	global_load_dwordx2 v[166:167], v140, s[10:11] offset:288
	v_add_u32_e32 v140, 0x20000, v143
	global_load_dwordx2 v[168:169], v140, s[10:11]
	global_load_dwordx2 v[170:171], v140, s[10:11] offset:32
	global_load_dwordx2 v[172:173], v140, s[10:11] offset:256
	global_load_dwordx2 v[174:175], v140, s[10:11] offset:288
	v_add_u32_e32 v140, 0x30000, v143
	global_load_dwordx2 v[176:177], v140, s[10:11]
	global_load_dwordx2 v[178:179], v140, s[10:11] offset:32
	global_load_dwordx2 v[180:181], v140, s[10:11] offset:256
	global_load_dwordx2 v[182:183], v140, s[10:11] offset:288
	v_add_u32_e32 v140, 0x80000, v143
	global_load_dwordx2 v[184:185], v140, s[10:11]
	global_load_dwordx2 v[186:187], v140, s[10:11] offset:32
	global_load_dwordx2 v[188:189], v140, s[10:11] offset:256
	global_load_dwordx2 v[190:191], v140, s[10:11] offset:288
	v_add_u32_e32 v140, 0x90000, v143
	global_load_dwordx2 v[192:193], v140, s[10:11]
	global_load_dwordx2 v[194:195], v140, s[10:11] offset:32
	global_load_dwordx2 v[196:197], v140, s[10:11] offset:256
	global_load_dwordx2 v[198:199], v140, s[10:11] offset:288
	v_add_u32_e32 v140, 0xa0000, v143
	global_load_dwordx2 v[200:201], v140, s[10:11]
	global_load_dwordx2 v[202:203], v140, s[10:11] offset:32
	global_load_dwordx2 v[204:205], v140, s[10:11] offset:256
	global_load_dwordx2 v[206:207], v140, s[10:11] offset:288
	v_add_u32_e32 v140, 0xb0000, v143
	global_load_dwordx2 v[208:209], v140, s[10:11]
	global_load_dwordx2 v[210:211], v140, s[10:11] offset:32
	global_load_dwordx2 v[212:213], v140, s[10:11] offset:256
	global_load_dwordx2 v[214:215], v140, s[10:11] offset:288
	s_and_b64 vcc, exec, s[12:13]
	s_cbranch_vccz .LBB0_1012
	s_barrier
